# norm loops: wave all-reduce via DPP adds (xor 1,2,4,8) + permlane16/32 swaps instead of 6 ds_bpermute round trips per row (strategy 7)
# speedup vs baseline: 1.0048x; 1.0048x over previous
.LBB0_262:
	v_lshl_add_u64 v[0:1], s[16:17], 0, v[18:19]
	v_add_co_u32_e32 v0, vcc, 0x3000000, v0
	s_waitcnt vmcnt(12)
	v_lshl_add_u64 v[36:37], s[12:13], 0, v[18:19]
	v_addc_co_u32_e32 v1, vcc, 0, v1, vcc
	global_load_dwordx2 v[2:3], v[0:1], off
	global_load_dwordx2 v[4:5], v[0:1], off offset:512
	global_load_dwordx2 v[6:7], v[0:1], off offset:1024
	global_load_dwordx2 v[28:29], v[0:1], off offset:1536
	global_load_dwordx2 v[30:31], v[0:1], off offset:2048
	global_load_dwordx2 v[32:33], v[0:1], off offset:2560
	global_load_dwordx2 v[34:35], v[0:1], off offset:3072
	s_nop 0
	global_load_dwordx2 v[0:1], v[0:1], off offset:3584
	v_add_co_u32_e32 v36, vcc, 0x3000000, v36
	s_add_i32 s18, s4, 2
	s_nop 0
	v_addc_co_u32_e32 v37, vcc, 0, v37, vcc
	global_load_dwordx2 v[38:39], v[36:37], off
	global_load_dwordx2 v[40:41], v[36:37], off offset:512
	global_load_dwordx2 v[42:43], v[36:37], off offset:1024
	global_load_dwordx2 v[46:47], v[36:37], off offset:1536
	global_load_dwordx2 v[48:49], v[36:37], off offset:2048
	global_load_dwordx2 v[50:51], v[36:37], off offset:2560
	global_load_dwordx2 v[52:53], v[36:37], off offset:3072
	s_nop 0
	global_load_dwordx2 v[36:37], v[36:37], off offset:3584
	s_ashr_i32 s19, s18, 31
	s_add_i32 s22, s4, 3
	s_lshl_b64 s[18:19], s[18:19], 12
	s_ashr_i32 s23, s22, 31
	v_lshl_add_u64 v[56:57], v[20:21], 0, s[18:19]
	s_lshl_b64 s[22:23], s[22:23], 12
	global_load_dwordx2 v[68:69], v[56:57], off
	global_load_dwordx2 v[70:71], v[56:57], off offset:512
	global_load_dwordx2 v[72:73], v[56:57], off offset:1024
	global_load_dwordx2 v[74:75], v[56:57], off offset:1536
	global_load_dwordx2 v[94:95], v[56:57], off offset:2048
	global_load_dwordx2 v[96:97], v[56:57], off offset:2560
	global_load_dwordx2 v[98:99], v[56:57], off offset:3072
	global_load_dwordx2 v[106:107], v[56:57], off offset:3584
	v_lshl_add_u64 v[56:57], v[20:21], 0, s[22:23]
	global_load_dwordx2 v[128:129], v[56:57], off
	global_load_dwordx2 v[130:131], v[56:57], off offset:512
	global_load_dwordx2 v[146:147], v[56:57], off offset:1024
	global_load_dwordx2 v[164:165], v[56:57], off offset:1536
	global_load_dwordx2 v[166:167], v[56:57], off offset:2048
	global_load_dwordx2 v[168:169], v[56:57], off offset:2560
	global_load_dwordx2 v[170:171], v[56:57], off offset:3072
	global_load_dwordx2 v[176:177], v[56:57], off offset:3584
	s_ashr_i32 s5, s4, 31
	s_lshr_b32 s5, s5, 20
	s_add_i32 s5, s4, s5
	s_ashr_i32 s5, s5, 12
	v_mad_i64_i32 v[230:231], vcc, s5, v237, v[22:23]
	v_mad_i64_i32 v[192:193], vcc, s5, v237, v[24:25]
	v_lshl_add_u64 v[250:251], v[230:231], 0, s[86:87]
	v_lshl_add_u64 v[252:253], v[192:193], 0, s[86:87]
	global_load_dwordx4 v[180:183], v[8:9], off
	global_load_dwordx4 v[184:187], v[230:231], off
	global_load_dwordx4 v[188:191], v[192:193], off
	global_load_dwordx4 v[196:199], v[8:9], off offset:1024
	global_load_dwordx4 v[200:203], v[230:231], off offset:1024
	global_load_dwordx4 v[204:207], v[192:193], off offset:1024
	global_load_dwordx4 v[208:211], v[8:9], off offset:2048
	global_load_dwordx4 v[212:215], v[230:231], off offset:2048
	global_load_dwordx4 v[218:221], v[192:193], off offset:2048
	global_load_dwordx4 v[222:225], v[8:9], off offset:3072
	global_load_dwordx4 v[226:229], v[230:231], off offset:3072
	global_load_dwordx4 v[242:245], v[192:193], off offset:3072
	s_add_i32 s4, s4, s6
	s_cmp_lt_i32 s4, s20
	s_waitcnt vmcnt(43)
	v_cvt_f32_f16_sdwa v163, v2 dst_sel:DWORD dst_unused:UNUSED_PAD src0_sel:WORD_1
	s_waitcnt vmcnt(42)
	v_cvt_f32_f16_sdwa v135, v4 dst_sel:DWORD dst_unused:UNUSED_PAD src0_sel:WORD_1
	v_cvt_f32_f16_sdwa v101, v3 dst_sel:DWORD dst_unused:UNUSED_PAD src0_sel:WORD_1
	v_cvt_f32_f16_e32 v162, v2
	v_cvt_f32_f16_sdwa v133, v5 dst_sel:DWORD dst_unused:UNUSED_PAD src0_sel:WORD_1
	v_cvt_f32_f16_e32 v134, v4
	v_cvt_f32_f16_e32 v100, v3
	v_cvt_f32_f16_e32 v132, v5
	s_waitcnt vmcnt(41)
	v_cvt_f32_f16_e32 v116, v6
	v_cvt_f32_f16_sdwa v117, v6 dst_sel:DWORD dst_unused:UNUSED_PAD src0_sel:WORD_1
	v_cvt_f32_f16_e32 v118, v7
	v_cvt_f32_f16_sdwa v119, v7 dst_sel:DWORD dst_unused:UNUSED_PAD src0_sel:WORD_1
	v_mov_b32_e32 v2, v163
	v_mov_b32_e32 v3, v135
	s_waitcnt vmcnt(40)
	v_cvt_f32_f16_e32 v108, v28
	v_cvt_f32_f16_sdwa v109, v28 dst_sel:DWORD dst_unused:UNUSED_PAD src0_sel:WORD_1
	v_cvt_f32_f16_e32 v110, v29
	v_cvt_f32_f16_sdwa v111, v29 dst_sel:DWORD dst_unused:UNUSED_PAD src0_sel:WORD_1
	s_waitcnt vmcnt(39)
	v_cvt_f32_f16_sdwa v87, v31 dst_sel:DWORD dst_unused:UNUSED_PAD src0_sel:WORD_1
	v_cvt_f32_f16_e32 v86, v31
	v_cvt_f32_f16_sdwa v85, v30 dst_sel:DWORD dst_unused:UNUSED_PAD src0_sel:WORD_1
	v_cvt_f32_f16_e32 v84, v30
	s_waitcnt vmcnt(36)
	v_cvt_f32_f16_sdwa v29, v1 dst_sel:DWORD dst_unused:UNUSED_PAD src0_sel:WORD_1
	v_cvt_f32_f16_e32 v28, v1
	v_cvt_f32_f16_sdwa v31, v0 dst_sel:DWORD dst_unused:UNUSED_PAD src0_sel:WORD_1
	v_cvt_f32_f16_e32 v30, v0
	v_mov_b32_e32 v0, v162
	v_mov_b32_e32 v1, v134
	v_pk_mul_f32 v[2:3], v[2:3], v[2:3]
	v_mov_b32_e32 v4, v101
	v_mov_b32_e32 v5, v133
	v_pk_fma_f32 v[0:1], v[0:1], v[0:1], v[2:3]
	v_mov_b32_e32 v2, v100
	v_mov_b32_e32 v3, v132
	v_pk_mul_f32 v[4:5], v[4:5], v[4:5]
	v_cvt_f32_f16_e32 v80, v32
	v_pk_fma_f32 v[2:3], v[2:3], v[2:3], v[4:5]
	v_pk_mul_f32 v[4:5], v[116:117], v[116:117]
	v_pk_add_f32 v[0:1], v[0:1], v[2:3]
	v_pk_mul_f32 v[2:3], v[118:119], v[118:119]
	v_pk_add_f32 v[0:1], v[0:1], v[0:1] op_sel:[0,1] op_sel_hi:[1,0]
	v_pk_mov_b32 v[6:7], v[4:5], v[2:3] op_sel:[1,0]
	v_mov_b32_e32 v5, v3
	v_pk_add_f32 v[2:3], v[6:7], v[4:5]
	v_mul_f32_e32 v4, v84, v84
	v_mul_f32_e32 v5, v85, v85
	v_pk_add_f32 v[2:3], v[2:3], v[2:3] op_sel:[0,1] op_sel_hi:[1,0]
	v_mov_b32_e32 v1, v4
	v_mov_b32_e32 v3, v5
	v_cvt_f32_f16_sdwa v81, v32 dst_sel:DWORD dst_unused:UNUSED_PAD src0_sel:WORD_1
	v_cvt_f32_f16_e32 v82, v33
	v_cvt_f32_f16_sdwa v83, v33 dst_sel:DWORD dst_unused:UNUSED_PAD src0_sel:WORD_1
	v_pk_add_f32 v[0:1], v[0:1], v[2:3]
	v_mul_f32_e32 v2, v109, v109
	v_mul_f32_e32 v4, v111, v111
	v_mul_f32_e32 v6, v86, v86
	v_mul_f32_e32 v7, v87, v87
	v_pk_fma_f32 v[2:3], v[108:109], v[108:109], v[2:3] op_sel_hi:[1,1,0]
	v_pk_fma_f32 v[4:5], v[110:111], v[110:111], v[4:5] op_sel_hi:[1,1,0]
	v_mov_b32_e32 v3, v6
	v_mov_b32_e32 v5, v7
	v_pk_add_f32 v[2:3], v[2:3], v[4:5]
	v_pk_mul_f32 v[4:5], v[80:81], v[80:81]
	v_pk_add_f32 v[0:1], v[0:1], v[2:3]
	v_pk_mul_f32 v[2:3], v[82:83], v[82:83]
	v_cvt_f32_f16_sdwa v57, v34 dst_sel:DWORD dst_unused:UNUSED_PAD src0_sel:WORD_1
	v_cvt_f32_f16_sdwa v59, v35 dst_sel:DWORD dst_unused:UNUSED_PAD src0_sel:WORD_1
	v_pk_mov_b32 v[6:7], v[4:5], v[2:3] op_sel:[1,0]
	v_mov_b32_e32 v5, v3
	v_cvt_f32_f16_e32 v56, v34
	v_cvt_f32_f16_e32 v58, v35
	v_pk_add_f32 v[2:3], v[6:7], v[4:5]
	v_mul_f32_e32 v4, v30, v30
	v_mul_f32_e32 v5, v31, v31
	v_pk_add_f32 v[0:1], v[0:1], v[0:1] op_sel:[0,1] op_sel_hi:[1,0]
	v_pk_add_f32 v[2:3], v[2:3], v[2:3] op_sel:[0,1] op_sel_hi:[1,0]
	v_mov_b32_e32 v1, v4
	v_mov_b32_e32 v3, v5
	v_pk_add_f32 v[0:1], v[0:1], v[2:3]
	v_mul_f32_e32 v2, v57, v57
	v_mul_f32_e32 v4, v59, v59
	v_mul_f32_e32 v6, v28, v28
	v_mul_f32_e32 v7, v29, v29
	v_pk_fma_f32 v[2:3], v[56:57], v[56:57], v[2:3] op_sel_hi:[1,1,0]
	v_pk_fma_f32 v[4:5], v[58:59], v[58:59], v[4:5] op_sel_hi:[1,1,0]
	v_mov_b32_e32 v3, v6
	v_mov_b32_e32 v5, v7
	v_pk_add_f32 v[2:3], v[2:3], v[4:5]
	s_waitcnt vmcnt(35)
	v_cvt_f32_f16_sdwa v161, v38 dst_sel:DWORD dst_unused:UNUSED_PAD src0_sel:WORD_1
	v_pk_add_f32 v[0:1], v[0:1], v[2:3]
	s_waitcnt vmcnt(34)
	v_cvt_f32_f16_sdwa v143, v40 dst_sel:DWORD dst_unused:UNUSED_PAD src0_sel:WORD_1
	v_add_f32_e32 v0, v0, v1
	v_cvt_f32_f16_sdwa v103, v39 dst_sel:DWORD dst_unused:UNUSED_PAD src0_sel:WORD_1
	v_cvt_f32_f16_e32 v160, v38
	v_cvt_f32_f16_sdwa v141, v41 dst_sel:DWORD dst_unused:UNUSED_PAD src0_sel:WORD_1
	v_cvt_f32_f16_e32 v142, v40
	s_waitcnt lgkmcnt(0)
	s_nop 1
	v_add_f32_dpp v0, v0, v0 quad_perm:[1,0,3,2] row_mask:0xf bank_mask:0xf
	v_cvt_f32_f16_e32 v102, v39
	v_cvt_f32_f16_e32 v140, v41
	s_waitcnt vmcnt(33)
	v_cvt_f32_f16_e32 v124, v42
	v_cvt_f32_f16_sdwa v125, v42 dst_sel:DWORD dst_unused:UNUSED_PAD src0_sel:WORD_1
	s_waitcnt lgkmcnt(0)
	s_nop 1
	v_add_f32_dpp v0, v0, v0 quad_perm:[2,3,0,1] row_mask:0xf bank_mask:0xf
	v_cvt_f32_f16_e32 v126, v43
	v_cvt_f32_f16_sdwa v127, v43 dst_sel:DWORD dst_unused:UNUSED_PAD src0_sel:WORD_1
	v_mov_b32_e32 v2, v161
	v_mov_b32_e32 v3, v143
	s_waitcnt lgkmcnt(0)
	s_nop 1
	v_add_f32_dpp v0, v0, v0 row_half_mirror row_mask:0xf bank_mask:0xf
	v_pk_mul_f32 v[2:3], v[2:3], v[2:3]
	v_mov_b32_e32 v4, v103
	v_mov_b32_e32 v5, v141
	v_pk_mul_f32 v[4:5], v[4:5], v[4:5]
	s_waitcnt lgkmcnt(0)
	s_nop 1
	v_add_f32_dpp v0, v0, v0 row_mirror row_mask:0xf bank_mask:0xf
	s_waitcnt vmcnt(31)
	v_cvt_f32_f16_sdwa v91, v48 dst_sel:DWORD dst_unused:UNUSED_PAD src0_sel:WORD_1
	v_cvt_f32_f16_e32 v90, v48
	v_cvt_f32_f16_sdwa v113, v46 dst_sel:DWORD dst_unused:UNUSED_PAD src0_sel:WORD_1
	v_cvt_f32_f16_sdwa v115, v47 dst_sel:DWORD dst_unused:UNUSED_PAD src0_sel:WORD_1
	s_waitcnt lgkmcnt(0)
	v_mov_b32_e32 v1, v0
	s_nop 1
	v_permlane16_swap_b32_e32 v0, v1
	s_nop 0
	v_add_f32_e32 v0, v0, v1
	v_cvt_f32_f16_e32 v112, v46
	v_cvt_f32_f16_e32 v114, v47
	v_cvt_f32_f16_sdwa v89, v49 dst_sel:DWORD dst_unused:UNUSED_PAD src0_sel:WORD_1
	v_cvt_f32_f16_e32 v88, v49
	s_waitcnt lgkmcnt(0)
	v_mov_b32_e32 v1, v0
	s_nop 1
	v_permlane32_swap_b32_e32 v0, v1
	s_nop 0
	v_add_f32_e32 v0, v0, v1
	v_fmamk_f32 v0, v0, 0x3a000000, v232
	v_rsq_f32_e32 v44, v0
	v_mov_b32_e32 v0, v160
	v_mov_b32_e32 v1, v142
	v_pk_fma_f32 v[0:1], v[0:1], v[0:1], v[2:3]
	v_mov_b32_e32 v2, v102
	v_mov_b32_e32 v3, v140
	v_pk_fma_f32 v[2:3], v[2:3], v[2:3], v[4:5]
	v_pk_mul_f32 v[4:5], v[124:125], v[124:125]
	v_pk_add_f32 v[0:1], v[0:1], v[2:3]
	v_pk_mul_f32 v[2:3], v[126:127], v[126:127]
	v_pk_add_f32 v[0:1], v[0:1], v[0:1] op_sel:[0,1] op_sel_hi:[1,0]
	v_pk_mov_b32 v[6:7], v[4:5], v[2:3] op_sel:[1,0]
	v_mov_b32_e32 v5, v3
	v_pk_add_f32 v[2:3], v[6:7], v[4:5]
	v_mul_f32_e32 v4, v90, v90
	v_mul_f32_e32 v5, v91, v91
	v_pk_add_f32 v[2:3], v[2:3], v[2:3] op_sel:[0,1] op_sel_hi:[1,0]
	v_mov_b32_e32 v1, v4
	v_mov_b32_e32 v3, v5
	s_waitcnt vmcnt(30)
	v_cvt_f32_f16_e32 v76, v50
	v_cvt_f32_f16_sdwa v77, v50 dst_sel:DWORD dst_unused:UNUSED_PAD src0_sel:WORD_1
	v_cvt_f32_f16_e32 v78, v51
	v_cvt_f32_f16_sdwa v79, v51 dst_sel:DWORD dst_unused:UNUSED_PAD src0_sel:WORD_1
	v_pk_add_f32 v[0:1], v[0:1], v[2:3]
	v_mul_f32_e32 v2, v113, v113
	v_mul_f32_e32 v4, v115, v115
	v_mul_f32_e32 v6, v88, v88
	v_mul_f32_e32 v7, v89, v89
	v_pk_fma_f32 v[2:3], v[112:113], v[112:113], v[2:3] op_sel_hi:[1,1,0]
	v_pk_fma_f32 v[4:5], v[114:115], v[114:115], v[4:5] op_sel_hi:[1,1,0]
	v_mov_b32_e32 v3, v6
	v_mov_b32_e32 v5, v7
	s_waitcnt vmcnt(28)
	v_cvt_f32_f16_sdwa v35, v36 dst_sel:DWORD dst_unused:UNUSED_PAD src0_sel:WORD_1
	v_cvt_f32_f16_e32 v34, v36
	v_pk_add_f32 v[2:3], v[2:3], v[4:5]
	v_pk_mul_f32 v[4:5], v[76:77], v[76:77]
	v_pk_add_f32 v[0:1], v[0:1], v[2:3]
	v_pk_mul_f32 v[2:3], v[78:79], v[78:79]
	v_cvt_f32_f16_sdwa v61, v52 dst_sel:DWORD dst_unused:UNUSED_PAD src0_sel:WORD_1
	v_cvt_f32_f16_sdwa v63, v53 dst_sel:DWORD dst_unused:UNUSED_PAD src0_sel:WORD_1
	v_pk_mov_b32 v[6:7], v[4:5], v[2:3] op_sel:[1,0]
	v_mov_b32_e32 v5, v3
	v_cvt_f32_f16_e32 v60, v52
	v_cvt_f32_f16_e32 v62, v53
	v_cvt_f32_f16_sdwa v33, v37 dst_sel:DWORD dst_unused:UNUSED_PAD src0_sel:WORD_1
	v_cvt_f32_f16_e32 v32, v37
	v_pk_add_f32 v[2:3], v[6:7], v[4:5]
	v_mul_f32_e32 v4, v34, v34
	v_mul_f32_e32 v5, v35, v35
	v_pk_add_f32 v[0:1], v[0:1], v[0:1] op_sel:[0,1] op_sel_hi:[1,0]
	v_pk_add_f32 v[2:3], v[2:3], v[2:3] op_sel:[0,1] op_sel_hi:[1,0]
	v_mov_b32_e32 v1, v4
	v_mov_b32_e32 v3, v5
	v_pk_add_f32 v[0:1], v[0:1], v[2:3]
	v_mul_f32_e32 v2, v61, v61
	v_mul_f32_e32 v4, v63, v63
	v_mul_f32_e32 v6, v32, v32
	v_mul_f32_e32 v7, v33, v33
	v_pk_fma_f32 v[2:3], v[60:61], v[60:61], v[2:3] op_sel_hi:[1,1,0]
	v_pk_fma_f32 v[4:5], v[62:63], v[62:63], v[4:5] op_sel_hi:[1,1,0]
	v_mov_b32_e32 v3, v6
	v_mov_b32_e32 v5, v7
	v_pk_add_f32 v[2:3], v[2:3], v[4:5]
	s_waitcnt vmcnt(27)
	v_cvt_f32_f16_sdwa v159, v68 dst_sel:DWORD dst_unused:UNUSED_PAD src0_sel:WORD_1
	v_pk_add_f32 v[0:1], v[0:1], v[2:3]
	s_waitcnt vmcnt(26)
	v_cvt_f32_f16_sdwa v151, v70 dst_sel:DWORD dst_unused:UNUSED_PAD src0_sel:WORD_1
	v_add_f32_e32 v0, v0, v1
	v_cvt_f32_f16_sdwa v105, v69 dst_sel:DWORD dst_unused:UNUSED_PAD src0_sel:WORD_1
	v_cvt_f32_f16_e32 v158, v68
	v_cvt_f32_f16_sdwa v149, v71 dst_sel:DWORD dst_unused:UNUSED_PAD src0_sel:WORD_1
	v_cvt_f32_f16_e32 v150, v70
	s_waitcnt lgkmcnt(0)
	s_nop 1
	v_add_f32_dpp v0, v0, v0 quad_perm:[1,0,3,2] row_mask:0xf bank_mask:0xf
	v_cvt_f32_f16_e32 v104, v69
	v_cvt_f32_f16_e32 v148, v71
	s_waitcnt vmcnt(25)
	v_cvt_f32_f16_e32 v136, v72
	v_cvt_f32_f16_sdwa v137, v72 dst_sel:DWORD dst_unused:UNUSED_PAD src0_sel:WORD_1
	s_waitcnt lgkmcnt(0)
	s_nop 1
	v_add_f32_dpp v0, v0, v0 quad_perm:[2,3,0,1] row_mask:0xf bank_mask:0xf
	v_cvt_f32_f16_e32 v138, v73
	v_cvt_f32_f16_sdwa v139, v73 dst_sel:DWORD dst_unused:UNUSED_PAD src0_sel:WORD_1
	v_mov_b32_e32 v2, v159
	v_mov_b32_e32 v3, v151
	s_waitcnt lgkmcnt(0)
	s_nop 1
	v_add_f32_dpp v0, v0, v0 row_half_mirror row_mask:0xf bank_mask:0xf
	v_pk_mul_f32 v[2:3], v[2:3], v[2:3]
	v_mov_b32_e32 v4, v105
	v_mov_b32_e32 v5, v149
	v_pk_mul_f32 v[4:5], v[4:5], v[4:5]
	s_waitcnt lgkmcnt(0)
	s_nop 1
	v_add_f32_dpp v0, v0, v0 row_mirror row_mask:0xf bank_mask:0xf
	s_waitcnt vmcnt(23)
	v_cvt_f32_f16_sdwa v93, v95 dst_sel:DWORD dst_unused:UNUSED_PAD src0_sel:WORD_1
	v_cvt_f32_f16_e32 v92, v95
	v_cvt_f32_f16_sdwa v95, v94 dst_sel:DWORD dst_unused:UNUSED_PAD src0_sel:WORD_1
	v_cvt_f32_f16_e32 v94, v94
	s_waitcnt lgkmcnt(0)
	v_mov_b32_e32 v1, v0
	s_nop 1
	v_permlane16_swap_b32_e32 v0, v1
	s_nop 0
	v_add_f32_e32 v0, v0, v1
	v_cvt_f32_f16_sdwa v121, v74 dst_sel:DWORD dst_unused:UNUSED_PAD src0_sel:WORD_1
	v_cvt_f32_f16_sdwa v123, v75 dst_sel:DWORD dst_unused:UNUSED_PAD src0_sel:WORD_1
	v_cvt_f32_f16_e32 v120, v74
	v_cvt_f32_f16_e32 v122, v75
	s_waitcnt lgkmcnt(0)
	v_mov_b32_e32 v1, v0
	s_nop 1
	v_permlane32_swap_b32_e32 v0, v1
	s_nop 0
	v_add_f32_e32 v0, v0, v1
	v_fmamk_f32 v0, v0, 0x3a000000, v232
	v_rsq_f32_e32 v54, v0
	v_mov_b32_e32 v0, v158
	v_mov_b32_e32 v1, v150
	v_pk_fma_f32 v[0:1], v[0:1], v[0:1], v[2:3]
	v_mov_b32_e32 v2, v104
	v_mov_b32_e32 v3, v148
	v_pk_fma_f32 v[2:3], v[2:3], v[2:3], v[4:5]
	v_pk_mul_f32 v[4:5], v[136:137], v[136:137]
	v_pk_add_f32 v[0:1], v[0:1], v[2:3]
	v_pk_mul_f32 v[2:3], v[138:139], v[138:139]
	v_pk_add_f32 v[0:1], v[0:1], v[0:1] op_sel:[0,1] op_sel_hi:[1,0]
	v_pk_mov_b32 v[6:7], v[4:5], v[2:3] op_sel:[1,0]
	v_mov_b32_e32 v5, v3
	v_pk_add_f32 v[2:3], v[6:7], v[4:5]
	v_mul_f32_e32 v4, v94, v94
	v_mul_f32_e32 v5, v95, v95
	v_pk_add_f32 v[2:3], v[2:3], v[2:3] op_sel:[0,1] op_sel_hi:[1,0]
	v_mov_b32_e32 v1, v4
	v_mov_b32_e32 v3, v5
	s_waitcnt vmcnt(22)
	v_cvt_f32_f16_e32 v72, v96
	v_cvt_f32_f16_sdwa v73, v96 dst_sel:DWORD dst_unused:UNUSED_PAD src0_sel:WORD_1
	v_cvt_f32_f16_e32 v74, v97
	v_cvt_f32_f16_sdwa v75, v97 dst_sel:DWORD dst_unused:UNUSED_PAD src0_sel:WORD_1
	v_pk_add_f32 v[0:1], v[0:1], v[2:3]
	v_mul_f32_e32 v2, v121, v121
	v_mul_f32_e32 v4, v123, v123
	v_mul_f32_e32 v6, v92, v92
	v_mul_f32_e32 v7, v93, v93
	v_pk_fma_f32 v[2:3], v[120:121], v[120:121], v[2:3] op_sel_hi:[1,1,0]
	v_pk_fma_f32 v[4:5], v[122:123], v[122:123], v[4:5] op_sel_hi:[1,1,0]
	v_mov_b32_e32 v3, v6
	v_mov_b32_e32 v5, v7
	s_waitcnt vmcnt(20)
	v_cvt_f32_f16_sdwa v39, v106 dst_sel:DWORD dst_unused:UNUSED_PAD src0_sel:WORD_1
	v_cvt_f32_f16_e32 v38, v106
	v_pk_add_f32 v[2:3], v[2:3], v[4:5]
	v_pk_mul_f32 v[4:5], v[72:73], v[72:73]
	v_pk_add_f32 v[0:1], v[0:1], v[2:3]
	v_pk_mul_f32 v[2:3], v[74:75], v[74:75]
	v_cvt_f32_f16_sdwa v51, v98 dst_sel:DWORD dst_unused:UNUSED_PAD src0_sel:WORD_1
	v_cvt_f32_f16_sdwa v53, v99 dst_sel:DWORD dst_unused:UNUSED_PAD src0_sel:WORD_1
	v_pk_mov_b32 v[6:7], v[4:5], v[2:3] op_sel:[1,0]
	v_mov_b32_e32 v5, v3
	v_cvt_f32_f16_e32 v50, v98
	v_cvt_f32_f16_e32 v52, v99
	v_cvt_f32_f16_sdwa v37, v107 dst_sel:DWORD dst_unused:UNUSED_PAD src0_sel:WORD_1
	v_cvt_f32_f16_e32 v36, v107
	v_pk_add_f32 v[2:3], v[6:7], v[4:5]
	v_mul_f32_e32 v4, v38, v38
	v_mul_f32_e32 v5, v39, v39
	v_pk_add_f32 v[0:1], v[0:1], v[0:1] op_sel:[0,1] op_sel_hi:[1,0]
	v_pk_add_f32 v[2:3], v[2:3], v[2:3] op_sel:[0,1] op_sel_hi:[1,0]
	v_mov_b32_e32 v1, v4
	v_mov_b32_e32 v3, v5
	v_pk_add_f32 v[0:1], v[0:1], v[2:3]
	v_mul_f32_e32 v2, v51, v51
	v_mul_f32_e32 v4, v53, v53
	v_mul_f32_e32 v6, v36, v36
	v_mul_f32_e32 v7, v37, v37
	v_pk_fma_f32 v[2:3], v[50:51], v[50:51], v[2:3] op_sel_hi:[1,1,0]
	v_pk_fma_f32 v[4:5], v[52:53], v[52:53], v[4:5] op_sel_hi:[1,1,0]
	v_mov_b32_e32 v3, v6
	v_mov_b32_e32 v5, v7
	v_pk_add_f32 v[2:3], v[2:3], v[4:5]
	s_waitcnt vmcnt(19)
	v_cvt_f32_f16_sdwa v157, v128 dst_sel:DWORD dst_unused:UNUSED_PAD src0_sel:WORD_1
	v_pk_add_f32 v[0:1], v[0:1], v[2:3]
	s_waitcnt vmcnt(18)
	v_cvt_f32_f16_sdwa v155, v130 dst_sel:DWORD dst_unused:UNUSED_PAD src0_sel:WORD_1
	v_add_f32_e32 v0, v0, v1
	v_cvt_f32_f16_sdwa v107, v129 dst_sel:DWORD dst_unused:UNUSED_PAD src0_sel:WORD_1
	v_cvt_f32_f16_e32 v156, v128
	v_cvt_f32_f16_sdwa v153, v131 dst_sel:DWORD dst_unused:UNUSED_PAD src0_sel:WORD_1
	v_cvt_f32_f16_e32 v154, v130
	s_waitcnt lgkmcnt(0)
	s_nop 1
	v_add_f32_dpp v0, v0, v0 quad_perm:[1,0,3,2] row_mask:0xf bank_mask:0xf
	v_cvt_f32_f16_e32 v106, v129
	v_cvt_f32_f16_e32 v152, v131
	s_waitcnt vmcnt(17)
	v_cvt_f32_f16_e32 v144, v146
	v_cvt_f32_f16_sdwa v145, v146 dst_sel:DWORD dst_unused:UNUSED_PAD src0_sel:WORD_1
	s_waitcnt lgkmcnt(0)
	s_nop 1
	v_add_f32_dpp v0, v0, v0 quad_perm:[2,3,0,1] row_mask:0xf bank_mask:0xf
	v_cvt_f32_f16_e32 v146, v147
	v_cvt_f32_f16_sdwa v147, v147 dst_sel:DWORD dst_unused:UNUSED_PAD src0_sel:WORD_1
	v_mov_b32_e32 v2, v157
	v_mov_b32_e32 v3, v155
	s_waitcnt lgkmcnt(0)
	s_nop 1
	v_add_f32_dpp v0, v0, v0 row_half_mirror row_mask:0xf bank_mask:0xf
	v_pk_mul_f32 v[2:3], v[2:3], v[2:3]
	v_mov_b32_e32 v4, v107
	v_mov_b32_e32 v5, v153
	v_pk_mul_f32 v[4:5], v[4:5], v[4:5]
	s_waitcnt lgkmcnt(0)
	s_nop 1
	v_add_f32_dpp v0, v0, v0 row_mirror row_mask:0xf bank_mask:0xf
	s_waitcnt vmcnt(15)
	v_cvt_f32_f16_sdwa v99, v166 dst_sel:DWORD dst_unused:UNUSED_PAD src0_sel:WORD_1
	v_cvt_f32_f16_e32 v98, v166
	v_cvt_f32_f16_sdwa v129, v164 dst_sel:DWORD dst_unused:UNUSED_PAD src0_sel:WORD_1
	v_cvt_f32_f16_sdwa v131, v165 dst_sel:DWORD dst_unused:UNUSED_PAD src0_sel:WORD_1
	s_waitcnt lgkmcnt(0)
	v_mov_b32_e32 v1, v0
	s_nop 1
	v_permlane16_swap_b32_e32 v0, v1
	s_nop 0
	v_add_f32_e32 v0, v0, v1
	v_cvt_f32_f16_e32 v128, v164
	v_cvt_f32_f16_e32 v130, v165
	v_cvt_f32_f16_sdwa v97, v167 dst_sel:DWORD dst_unused:UNUSED_PAD src0_sel:WORD_1
	v_cvt_f32_f16_e32 v96, v167
	s_waitcnt lgkmcnt(0)
	v_mov_b32_e32 v1, v0
	s_nop 1
	v_permlane32_swap_b32_e32 v0, v1
	s_nop 0
	v_add_f32_e32 v0, v0, v1
	v_fmamk_f32 v0, v0, 0x3a000000, v232
	v_rsq_f32_e32 v64, v0
	v_mov_b32_e32 v0, v156
	v_mov_b32_e32 v1, v154
	v_pk_fma_f32 v[0:1], v[0:1], v[0:1], v[2:3]
	v_mov_b32_e32 v2, v106
	v_mov_b32_e32 v3, v152
	v_pk_fma_f32 v[2:3], v[2:3], v[2:3], v[4:5]
	v_pk_mul_f32 v[4:5], v[144:145], v[144:145]
	v_pk_add_f32 v[0:1], v[0:1], v[2:3]
	v_pk_mul_f32 v[2:3], v[146:147], v[146:147]
	v_pk_add_f32 v[0:1], v[0:1], v[0:1] op_sel:[0,1] op_sel_hi:[1,0]
	v_pk_mov_b32 v[6:7], v[4:5], v[2:3] op_sel:[1,0]
	v_mov_b32_e32 v5, v3
	v_pk_add_f32 v[2:3], v[6:7], v[4:5]
	v_mul_f32_e32 v4, v98, v98
	v_mul_f32_e32 v5, v99, v99
	v_pk_add_f32 v[2:3], v[2:3], v[2:3] op_sel:[0,1] op_sel_hi:[1,0]
	v_mov_b32_e32 v1, v4
	v_mov_b32_e32 v3, v5
	s_waitcnt vmcnt(14)
	v_cvt_f32_f16_e32 v68, v168
	v_cvt_f32_f16_sdwa v69, v168 dst_sel:DWORD dst_unused:UNUSED_PAD src0_sel:WORD_1
	v_cvt_f32_f16_e32 v70, v169
	v_cvt_f32_f16_sdwa v71, v169 dst_sel:DWORD dst_unused:UNUSED_PAD src0_sel:WORD_1
	v_pk_add_f32 v[0:1], v[0:1], v[2:3]
	v_mul_f32_e32 v2, v129, v129
	v_mul_f32_e32 v4, v131, v131
	v_mul_f32_e32 v6, v96, v96
	v_mul_f32_e32 v7, v97, v97
	v_pk_fma_f32 v[2:3], v[128:129], v[128:129], v[2:3] op_sel_hi:[1,1,0]
	v_pk_fma_f32 v[4:5], v[130:131], v[130:131], v[4:5] op_sel_hi:[1,1,0]
	v_mov_b32_e32 v3, v6
	v_mov_b32_e32 v5, v7
	s_waitcnt vmcnt(12)
	v_cvt_f32_f16_sdwa v43, v176 dst_sel:DWORD dst_unused:UNUSED_PAD src0_sel:WORD_1
	v_cvt_f32_f16_e32 v42, v176
	v_pk_add_f32 v[2:3], v[2:3], v[4:5]
	v_pk_mul_f32 v[4:5], v[68:69], v[68:69]
	v_pk_add_f32 v[0:1], v[0:1], v[2:3]
	v_pk_mul_f32 v[2:3], v[70:71], v[70:71]
	v_cvt_f32_f16_sdwa v47, v170 dst_sel:DWORD dst_unused:UNUSED_PAD src0_sel:WORD_1
	v_cvt_f32_f16_sdwa v49, v171 dst_sel:DWORD dst_unused:UNUSED_PAD src0_sel:WORD_1
	v_pk_mov_b32 v[6:7], v[4:5], v[2:3] op_sel:[1,0]
	v_mov_b32_e32 v5, v3
	v_cvt_f32_f16_e32 v46, v170
	v_cvt_f32_f16_e32 v48, v171
	v_cvt_f32_f16_sdwa v41, v177 dst_sel:DWORD dst_unused:UNUSED_PAD src0_sel:WORD_1
	v_cvt_f32_f16_e32 v40, v177
	v_pk_add_f32 v[2:3], v[6:7], v[4:5]
	v_mul_f32_e32 v4, v42, v42
	v_mul_f32_e32 v5, v43, v43
	v_pk_add_f32 v[0:1], v[0:1], v[0:1] op_sel:[0,1] op_sel_hi:[1,0]
	v_pk_add_f32 v[2:3], v[2:3], v[2:3] op_sel:[0,1] op_sel_hi:[1,0]
	v_mov_b32_e32 v1, v4
	v_mov_b32_e32 v3, v5
	v_pk_add_f32 v[0:1], v[0:1], v[2:3]
	v_mul_f32_e32 v2, v47, v47
	v_mul_f32_e32 v4, v49, v49
	v_mul_f32_e32 v6, v40, v40
	v_mul_f32_e32 v7, v41, v41
	v_pk_fma_f32 v[2:3], v[46:47], v[46:47], v[2:3] op_sel_hi:[1,1,0]
	v_pk_fma_f32 v[4:5], v[48:49], v[48:49], v[4:5] op_sel_hi:[1,1,0]
	v_mov_b32_e32 v3, v6
	v_mov_b32_e32 v5, v7
	v_pk_add_f32 v[2:3], v[2:3], v[4:5]
	v_mad_i64_i32 v[166:167], s[52:53], s5, v237, v[22:23]
	v_pk_add_f32 v[0:1], v[0:1], v[2:3]
	v_mad_i64_i32 v[164:165], s[52:53], s5, v237, v[24:25]
	v_add_f32_e32 v0, v0, v1
	v_pk_mul_f32 v[100:101], v[44:45], v[100:101] op_sel_hi:[0,1]
	v_pk_mul_f32 v[162:163], v[44:45], v[162:163] op_sel_hi:[0,1]
	v_pk_mul_f32 v[102:103], v[54:55], v[102:103] op_sel_hi:[0,1]
	v_pk_mul_f32 v[160:161], v[54:55], v[160:161] op_sel_hi:[0,1]
	s_waitcnt lgkmcnt(0)
	s_nop 1
	v_add_f32_dpp v0, v0, v0 quad_perm:[1,0,3,2] row_mask:0xf bank_mask:0xf
	v_pk_mul_f32 v[104:105], v[64:65], v[104:105] op_sel_hi:[0,1]
	v_pk_mul_f32 v[158:159], v[64:65], v[158:159] op_sel_hi:[0,1]
	v_pk_mul_f32 v[132:133], v[44:45], v[132:133] op_sel_hi:[0,1]
	v_pk_mul_f32 v[134:135], v[44:45], v[134:135] op_sel_hi:[0,1]
	s_waitcnt lgkmcnt(0)
	s_nop 1
	v_add_f32_dpp v0, v0, v0 quad_perm:[2,3,0,1] row_mask:0xf bank_mask:0xf
	v_pk_mul_f32 v[118:119], v[44:45], v[118:119] op_sel_hi:[0,1]
	v_pk_mul_f32 v[116:117], v[44:45], v[116:117] op_sel_hi:[0,1]
	v_pk_mul_f32 v[110:111], v[44:45], v[110:111] op_sel_hi:[0,1]
	v_pk_mul_f32 v[108:109], v[44:45], v[108:109] op_sel_hi:[0,1]
	s_waitcnt lgkmcnt(0)
	s_nop 1
	v_add_f32_dpp v0, v0, v0 row_half_mirror row_mask:0xf bank_mask:0xf
	v_pk_mul_f32 v[86:87], v[44:45], v[86:87] op_sel_hi:[0,1]
	v_pk_mul_f32 v[84:85], v[44:45], v[84:85] op_sel_hi:[0,1]
	v_pk_mul_f32 v[82:83], v[44:45], v[82:83] op_sel_hi:[0,1]
	v_pk_mul_f32 v[80:81], v[44:45], v[80:81] op_sel_hi:[0,1]
	s_waitcnt lgkmcnt(0)
	s_nop 1
	v_add_f32_dpp v0, v0, v0 row_mirror row_mask:0xf bank_mask:0xf
	v_pk_mul_f32 v[78:79], v[54:55], v[78:79] op_sel_hi:[0,1]
	v_pk_mul_f32 v[76:77], v[54:55], v[76:77] op_sel_hi:[0,1]
	v_pk_mul_f32 v[74:75], v[64:65], v[74:75] op_sel_hi:[0,1]
	v_pk_mul_f32 v[72:73], v[64:65], v[72:73] op_sel_hi:[0,1]
	s_waitcnt lgkmcnt(0)
	v_mov_b32_e32 v1, v0
	s_nop 1
	v_permlane16_swap_b32_e32 v0, v1
	s_nop 0
	v_add_f32_e32 v0, v0, v1
	v_pk_mul_f32 v[58:59], v[44:45], v[58:59] op_sel_hi:[0,1]
	v_pk_mul_f32 v[56:57], v[44:45], v[56:57] op_sel_hi:[0,1]
	v_pk_mul_f32 v[52:53], v[64:65], v[52:53] op_sel_hi:[0,1]
	v_pk_mul_f32 v[50:51], v[64:65], v[50:51] op_sel_hi:[0,1]
	s_waitcnt lgkmcnt(0)
	v_mov_b32_e32 v1, v0
	s_nop 1
	v_permlane32_swap_b32_e32 v0, v1
	s_nop 0
	v_add_f32_e32 v0, v0, v1
	v_fmamk_f32 v0, v0, 0x3a000000, v232
	v_rsq_f32_e32 v66, v0
	v_pk_mul_f32 v[28:29], v[44:45], v[28:29] op_sel_hi:[0,1]
	v_pk_mul_f32 v[30:31], v[44:45], v[30:31] op_sel_hi:[0,1]
	v_pk_mul_f32 v[106:107], v[66:67], v[106:107] op_sel_hi:[0,1]
	v_pk_mul_f32 v[156:157], v[66:67], v[156:157] op_sel_hi:[0,1]
	v_pk_mul_f32 v[70:71], v[66:67], v[70:71] op_sel_hi:[0,1]
	v_pk_mul_f32 v[68:69], v[66:67], v[68:69] op_sel_hi:[0,1]
	v_pk_mul_f32 v[48:49], v[66:67], v[48:49] op_sel_hi:[0,1]
	v_pk_mul_f32 v[46:47], v[66:67], v[46:47] op_sel_hi:[0,1]
	s_waitcnt vmcnt(9)
	v_pk_mul_f32 v[162:163], v[162:163], v[180:181]
	v_pk_mul_f32 v[100:101], v[100:101], v[182:183]
	v_pk_add_f32 v[168:169], v[190:191], 1.0 op_sel_hi:[1,0]
	v_pk_add_f32 v[170:171], v[188:189], 1.0 op_sel_hi:[1,0]
	v_pk_fma_f32 v[100:101], v[100:101], v[168:169], v[186:187]
	v_pk_fma_f32 v[162:163], v[162:163], v[170:171], v[184:185]
	v_pk_mul_f32 v[160:161], v[160:161], v[180:181]
	v_cvt_pk_bf16_f32 v162, v162, v163
	v_cvt_pk_bf16_f32 v163, v100, v101
	v_lshl_add_u64 v[100:101], s[14:15], 0, v[18:19]
	v_pk_mul_f32 v[102:103], v[102:103], v[182:183]
	v_add_co_u32_e32 v100, vcc, s30, v100
	v_pk_fma_f32 v[102:103], v[102:103], v[168:169], v[186:187]
	v_pk_fma_f32 v[160:161], v[160:161], v[170:171], v[184:185]
	v_addc_co_u32_e32 v101, vcc, 0, v101, vcc
	v_cvt_pk_bf16_f32 v160, v160, v161
	v_cvt_pk_bf16_f32 v161, v102, v103
	v_lshl_add_u64 v[102:103], s[8:9], 0, v[18:19]
	v_pk_mul_f32 v[158:159], v[180:181], v[158:159]
	v_pk_mul_f32 v[104:105], v[182:183], v[104:105]
	v_pk_mul_f32 v[180:181], v[180:181], v[156:157]
	v_pk_mul_f32 v[182:183], v[182:183], v[106:107]
	v_add_co_u32_e32 v102, vcc, s30, v102
	v_pk_fma_f32 v[104:105], v[104:105], v[168:169], v[186:187]
	v_pk_fma_f32 v[158:159], v[158:159], v[170:171], v[184:185]
	v_pk_fma_f32 v[186:187], v[168:169], v[182:183], v[186:187]
	v_pk_fma_f32 v[184:185], v[170:171], v[180:181], v[184:185]
	v_addc_co_u32_e32 v103, vcc, 0, v103, vcc
	v_cvt_pk_bf16_f32 v158, v158, v159
	v_cvt_pk_bf16_f32 v159, v104, v105
	v_lshl_add_u64 v[104:105], v[26:27], 0, s[18:19]
	v_cvt_pk_bf16_f32 v184, v184, v185
	v_cvt_pk_bf16_f32 v185, v186, v187
	v_lshl_add_u64 v[106:107], v[26:27], 0, s[22:23]
	global_store_dwordx2 v[100:101], v[162:163], off
	global_store_dwordx2 v[102:103], v[160:161], off
	global_store_dwordx2 v[104:105], v[158:159], off
	global_store_dwordx2 v[106:107], v[184:185], off
	global_load_dwordx4 v[180:183], v[10:11], off
	global_load_dwordx4 v[184:187], v[252:253], off
	global_load_dwordx4 v[188:191], v[250:251], off
	s_nop 0
	s_cselect_b64 s[18:19], -1, 0
	s_add_u32 s8, s8, s10
	s_addc_u32 s9, s9, s11
	s_add_u32 s12, s12, s10
	s_addc_u32 s13, s13, s11
	s_add_u32 s14, s14, s10
	s_addc_u32 s15, s15, s11
	s_add_u32 s16, s16, s10
	s_addc_u32 s17, s17, s11
	s_waitcnt vmcnt(13)
	v_pk_mul_f32 v[134:135], v[134:135], v[196:197]
	v_pk_mul_f32 v[132:133], v[132:133], v[198:199]
	v_pk_add_f32 v[206:207], v[206:207], 1.0 op_sel_hi:[1,0]
	v_pk_add_f32 v[204:205], v[204:205], 1.0 op_sel_hi:[1,0]
	v_pk_fma_f32 v[132:133], v[132:133], v[206:207], v[202:203]
	v_pk_fma_f32 v[134:135], v[134:135], v[204:205], v[200:201]
	s_nop 0
	v_cvt_pk_bf16_f32 v134, v134, v135
	v_cvt_pk_bf16_f32 v135, v132, v133
	global_store_dwordx2 v[100:101], v[134:135], off offset:512
	v_pk_mul_f32 v[132:133], v[54:55], v[140:141] op_sel_hi:[0,1]
	v_pk_mul_f32 v[134:135], v[54:55], v[142:143] op_sel_hi:[0,1]
	v_pk_mul_f32 v[134:135], v[134:135], v[196:197]
	v_pk_mul_f32 v[132:133], v[132:133], v[198:199]
	v_pk_fma_f32 v[134:135], v[134:135], v[204:205], v[200:201]
	v_pk_fma_f32 v[132:133], v[132:133], v[206:207], v[202:203]
	v_cvt_pk_bf16_f32 v134, v134, v135
	v_cvt_pk_bf16_f32 v135, v132, v133
	global_store_dwordx2 v[102:103], v[134:135], off offset:512
	v_pk_mul_f32 v[132:133], v[64:65], v[148:149] op_sel_hi:[0,1]
	v_pk_mul_f32 v[134:135], v[64:65], v[150:151] op_sel_hi:[0,1]
	v_pk_mul_f32 v[134:135], v[134:135], v[196:197]
	v_pk_mul_f32 v[132:133], v[132:133], v[198:199]
	v_pk_fma_f32 v[134:135], v[134:135], v[204:205], v[200:201]
	v_pk_fma_f32 v[132:133], v[132:133], v[206:207], v[202:203]
	v_cvt_pk_bf16_f32 v134, v134, v135
	v_cvt_pk_bf16_f32 v135, v132, v133
	global_store_dwordx2 v[104:105], v[134:135], off offset:512
	v_pk_mul_f32 v[132:133], v[66:67], v[152:153] op_sel_hi:[0,1]
	v_pk_mul_f32 v[134:135], v[66:67], v[154:155] op_sel_hi:[0,1]
	v_pk_mul_f32 v[196:197], v[196:197], v[134:135]
	v_pk_mul_f32 v[198:199], v[198:199], v[132:133]
	v_pk_fma_f32 v[196:197], v[196:197], v[204:205], v[200:201]
	v_pk_fma_f32 v[198:199], v[198:199], v[206:207], v[202:203]
	v_cvt_pk_bf16_f32 v196, v196, v197
	v_cvt_pk_bf16_f32 v197, v198, v199
	global_store_dwordx2 v[106:107], v[196:197], off offset:512
	global_load_dwordx4 v[196:199], v[12:13], off
	global_load_dwordx4 v[200:203], v[250:251], off offset:1024
	global_load_dwordx4 v[204:207], v[252:253], off offset:1024
	s_nop 0
	s_waitcnt vmcnt(17)
	v_pk_mul_f32 v[116:117], v[116:117], v[208:209]
	v_pk_mul_f32 v[118:119], v[118:119], v[210:211]
	v_pk_add_f32 v[220:221], v[220:221], 1.0 op_sel_hi:[1,0]
	v_pk_add_f32 v[218:219], v[218:219], 1.0 op_sel_hi:[1,0]
	v_pk_fma_f32 v[118:119], v[118:119], v[220:221], v[214:215]
	v_pk_fma_f32 v[116:117], v[116:117], v[218:219], v[212:213]
	s_nop 0
	v_cvt_pk_bf16_f32 v116, v116, v117
	v_cvt_pk_bf16_f32 v117, v118, v119
	global_store_dwordx2 v[100:101], v[116:117], off offset:1024
	v_pk_mul_f32 v[116:117], v[54:55], v[126:127] op_sel_hi:[0,1]
	v_pk_mul_f32 v[118:119], v[54:55], v[124:125] op_sel_hi:[0,1]
	v_pk_mul_f32 v[118:119], v[118:119], v[208:209]
	v_pk_mul_f32 v[116:117], v[116:117], v[210:211]
	v_pk_fma_f32 v[118:119], v[118:119], v[218:219], v[212:213]
	v_pk_fma_f32 v[116:117], v[116:117], v[220:221], v[214:215]
	v_cvt_pk_bf16_f32 v118, v118, v119
	v_cvt_pk_bf16_f32 v119, v116, v117
	global_store_dwordx2 v[102:103], v[118:119], off offset:1024
	v_pk_mul_f32 v[116:117], v[64:65], v[138:139] op_sel_hi:[0,1]
	v_pk_mul_f32 v[118:119], v[64:65], v[136:137] op_sel_hi:[0,1]
	v_pk_mul_f32 v[118:119], v[118:119], v[208:209]
	v_pk_mul_f32 v[116:117], v[116:117], v[210:211]
	v_pk_fma_f32 v[118:119], v[118:119], v[218:219], v[212:213]
	v_pk_fma_f32 v[116:117], v[116:117], v[220:221], v[214:215]
	v_cvt_pk_bf16_f32 v118, v118, v119
	v_cvt_pk_bf16_f32 v119, v116, v117
	global_store_dwordx2 v[104:105], v[118:119], off offset:1024
	v_pk_mul_f32 v[116:117], v[66:67], v[146:147] op_sel_hi:[0,1]
	v_pk_mul_f32 v[118:119], v[66:67], v[144:145] op_sel_hi:[0,1]
	v_pk_mul_f32 v[208:209], v[118:119], v[208:209]
	v_pk_mul_f32 v[210:211], v[116:117], v[210:211]
	v_pk_fma_f32 v[208:209], v[208:209], v[218:219], v[212:213]
	v_pk_fma_f32 v[210:211], v[210:211], v[220:221], v[214:215]
	v_cvt_pk_bf16_f32 v208, v208, v209
	v_cvt_pk_bf16_f32 v209, v210, v211
	global_store_dwordx2 v[106:107], v[208:209], off offset:1024
	global_load_dwordx4 v[208:211], v[14:15], off
	global_load_dwordx4 v[212:215], v[250:251], off offset:2048
	global_load_dwordx4 v[218:221], v[252:253], off offset:2048
	s_nop 0
	s_waitcnt vmcnt(21)
	v_pk_mul_f32 v[108:109], v[108:109], v[222:223]
	v_pk_mul_f32 v[110:111], v[110:111], v[224:225]
	v_pk_add_f32 v[244:245], v[244:245], 1.0 op_sel_hi:[1,0]
	v_pk_add_f32 v[242:243], v[242:243], 1.0 op_sel_hi:[1,0]
	v_pk_fma_f32 v[110:111], v[110:111], v[244:245], v[228:229]
	v_pk_fma_f32 v[108:109], v[108:109], v[242:243], v[226:227]
	s_nop 0
	v_cvt_pk_bf16_f32 v108, v108, v109
	v_cvt_pk_bf16_f32 v109, v110, v111
	global_store_dwordx2 v[100:101], v[108:109], off offset:1536
	v_pk_mul_f32 v[108:109], v[54:55], v[114:115] op_sel_hi:[0,1]
	v_pk_mul_f32 v[110:111], v[54:55], v[112:113] op_sel_hi:[0,1]
	v_pk_mul_f32 v[110:111], v[110:111], v[222:223]
	v_pk_mul_f32 v[108:109], v[108:109], v[224:225]
	v_pk_fma_f32 v[110:111], v[110:111], v[242:243], v[226:227]
	v_pk_fma_f32 v[108:109], v[108:109], v[244:245], v[228:229]
	v_cvt_pk_bf16_f32 v110, v110, v111
	v_cvt_pk_bf16_f32 v111, v108, v109
	global_store_dwordx2 v[102:103], v[110:111], off offset:1536
	v_pk_mul_f32 v[108:109], v[64:65], v[122:123] op_sel_hi:[0,1]
	v_pk_mul_f32 v[110:111], v[64:65], v[120:121] op_sel_hi:[0,1]
	v_pk_mul_f32 v[110:111], v[110:111], v[222:223]
	v_pk_mul_f32 v[108:109], v[108:109], v[224:225]
	v_pk_fma_f32 v[110:111], v[110:111], v[242:243], v[226:227]
	v_pk_fma_f32 v[108:109], v[108:109], v[244:245], v[228:229]
	v_cvt_pk_bf16_f32 v110, v110, v111
	v_cvt_pk_bf16_f32 v111, v108, v109
	global_store_dwordx2 v[104:105], v[110:111], off offset:1536
	v_pk_mul_f32 v[108:109], v[66:67], v[130:131] op_sel_hi:[0,1]
	v_pk_mul_f32 v[110:111], v[66:67], v[128:129] op_sel_hi:[0,1]
	v_pk_mul_f32 v[222:223], v[110:111], v[222:223]
	v_pk_mul_f32 v[224:225], v[108:109], v[224:225]
	v_add_co_u32_e32 v108, vcc, s77, v166
	v_pk_fma_f32 v[224:225], v[224:225], v[244:245], v[228:229]
	v_pk_fma_f32 v[222:223], v[222:223], v[242:243], v[226:227]
	v_addc_co_u32_e32 v109, vcc, 0, v167, vcc
	v_cvt_pk_bf16_f32 v222, v222, v223
	v_cvt_pk_bf16_f32 v223, v224, v225
	v_add_co_u32_e32 v110, vcc, s77, v164
	global_store_dwordx2 v[106:107], v[222:223], off offset:1536
	global_load_dwordx4 v[222:225], v[16:17], off
	global_load_dwordx4 v[226:229], v[250:251], off offset:3072
	global_load_dwordx4 v[242:245], v[252:253], off offset:3072
	s_nop 0
	v_addc_co_u32_e32 v111, vcc, 0, v165, vcc
	v_subrev_co_u32_e32 v174, vcc, 1, v174
	s_waitcnt vmcnt(21)
	v_pk_mul_f32 v[84:85], v[84:85], v[180:181]
	v_pk_add_f32 v[112:113], v[186:187], 1.0 op_sel_hi:[1,0]
	v_pk_add_f32 v[184:185], v[184:185], 1.0 op_sel_hi:[1,0]
	v_pk_mul_f32 v[86:87], v[86:87], v[182:183]
	v_pk_fma_f32 v[84:85], v[84:85], v[184:185], v[188:189]
	v_pk_fma_f32 v[86:87], v[86:87], v[112:113], v[190:191]
	v_cvt_pk_bf16_f32 v84, v84, v85
	v_cvt_pk_bf16_f32 v85, v86, v87
	global_store_dwordx2 v[100:101], v[84:85], off offset:2048
	v_pk_mul_f32 v[84:85], v[54:55], v[88:89] op_sel_hi:[0,1]
	v_pk_mul_f32 v[86:87], v[54:55], v[90:91] op_sel_hi:[0,1]
	v_pk_mul_f32 v[86:87], v[86:87], v[180:181]
	v_pk_mul_f32 v[84:85], v[84:85], v[182:183]
	v_pk_fma_f32 v[86:87], v[86:87], v[184:185], v[188:189]
	v_pk_fma_f32 v[84:85], v[84:85], v[112:113], v[190:191]
	v_cvt_pk_bf16_f32 v86, v86, v87
	v_cvt_pk_bf16_f32 v87, v84, v85
	global_store_dwordx2 v[102:103], v[86:87], off offset:2048
	v_pk_mul_f32 v[84:85], v[64:65], v[92:93] op_sel_hi:[0,1]
	v_pk_mul_f32 v[86:87], v[64:65], v[94:95] op_sel_hi:[0,1]
	v_pk_mul_f32 v[86:87], v[86:87], v[180:181]
	v_pk_mul_f32 v[84:85], v[84:85], v[182:183]
	v_pk_fma_f32 v[86:87], v[86:87], v[184:185], v[188:189]
	v_pk_fma_f32 v[84:85], v[84:85], v[112:113], v[190:191]
	v_cvt_pk_bf16_f32 v86, v86, v87
	v_cvt_pk_bf16_f32 v87, v84, v85
	global_store_dwordx2 v[104:105], v[86:87], off offset:2048
	v_pk_mul_f32 v[84:85], v[66:67], v[96:97] op_sel_hi:[0,1]
	v_pk_mul_f32 v[86:87], v[66:67], v[98:99] op_sel_hi:[0,1]
	v_pk_mul_f32 v[180:181], v[86:87], v[180:181]
	v_pk_mul_f32 v[182:183], v[84:85], v[182:183]
	v_pk_fma_f32 v[180:181], v[180:181], v[184:185], v[188:189]
	v_pk_fma_f32 v[182:183], v[182:183], v[112:113], v[190:191]
	v_cvt_pk_bf16_f32 v180, v180, v181
	v_cvt_pk_bf16_f32 v181, v182, v183
	global_store_dwordx2 v[106:107], v[180:181], off offset:2048
	s_nop 0
	s_waitcnt vmcnt(18)
	v_pk_mul_f32 v[80:81], v[80:81], v[196:197]
	v_pk_mul_f32 v[82:83], v[82:83], v[198:199]
	v_pk_add_f32 v[84:85], v[206:207], 1.0 op_sel_hi:[1,0]
	v_pk_add_f32 v[204:205], v[204:205], 1.0 op_sel_hi:[1,0]
	v_pk_mul_f32 v[76:77], v[76:77], v[196:197]
	v_pk_mul_f32 v[78:79], v[78:79], v[198:199]
	v_pk_mul_f32 v[72:73], v[72:73], v[196:197]
	v_pk_mul_f32 v[74:75], v[74:75], v[198:199]
	v_pk_mul_f32 v[196:197], v[68:69], v[196:197]
	v_pk_mul_f32 v[198:199], v[70:71], v[198:199]
	v_pk_fma_f32 v[82:83], v[82:83], v[84:85], v[202:203]
	v_pk_fma_f32 v[80:81], v[80:81], v[204:205], v[200:201]
	v_pk_fma_f32 v[78:79], v[78:79], v[84:85], v[202:203]
	v_pk_fma_f32 v[76:77], v[76:77], v[204:205], v[200:201]
	v_pk_fma_f32 v[74:75], v[74:75], v[84:85], v[202:203]
	v_pk_fma_f32 v[72:73], v[72:73], v[204:205], v[200:201]
	v_pk_fma_f32 v[202:203], v[198:199], v[84:85], v[202:203]
	v_pk_fma_f32 v[200:201], v[196:197], v[204:205], v[200:201]
	v_cvt_pk_bf16_f32 v80, v80, v81
	v_cvt_pk_bf16_f32 v81, v82, v83
	v_cvt_pk_bf16_f32 v76, v76, v77
	v_cvt_pk_bf16_f32 v77, v78, v79
	v_cvt_pk_bf16_f32 v72, v72, v73
	v_cvt_pk_bf16_f32 v73, v74, v75
	v_cvt_pk_bf16_f32 v200, v200, v201
	v_cvt_pk_bf16_f32 v201, v202, v203
	global_store_dwordx2 v[100:101], v[80:81], off offset:2560
	global_store_dwordx2 v[102:103], v[76:77], off offset:2560
	global_store_dwordx2 v[104:105], v[72:73], off offset:2560
	global_store_dwordx2 v[106:107], v[200:201], off offset:2560
	s_nop 0
	s_waitcnt vmcnt(15)
	v_pk_mul_f32 v[56:57], v[56:57], v[208:209]
	v_pk_mul_f32 v[58:59], v[58:59], v[210:211]
	v_pk_add_f32 v[220:221], v[220:221], 1.0 op_sel_hi:[1,0]
	v_pk_add_f32 v[218:219], v[218:219], 1.0 op_sel_hi:[1,0]
	v_pk_fma_f32 v[58:59], v[58:59], v[220:221], v[214:215]
	v_pk_fma_f32 v[56:57], v[56:57], v[218:219], v[212:213]
	v_pk_mul_f32 v[50:51], v[50:51], v[208:209]
	v_cvt_pk_bf16_f32 v56, v56, v57
	v_cvt_pk_bf16_f32 v57, v58, v59
	global_store_dwordx2 v[100:101], v[56:57], off offset:3072
	v_pk_mul_f32 v[56:57], v[54:55], v[62:63] op_sel_hi:[0,1]
	v_pk_mul_f32 v[58:59], v[54:55], v[60:61] op_sel_hi:[0,1]
	v_pk_mul_f32 v[58:59], v[58:59], v[208:209]
	v_pk_mul_f32 v[56:57], v[56:57], v[210:211]
	v_pk_mul_f32 v[52:53], v[52:53], v[210:211]
	v_pk_mul_f32 v[208:209], v[46:47], v[208:209]
	v_pk_mul_f32 v[210:211], v[48:49], v[210:211]
	v_pk_fma_f32 v[56:57], v[56:57], v[220:221], v[214:215]
	v_pk_fma_f32 v[58:59], v[58:59], v[218:219], v[212:213]
	v_pk_fma_f32 v[52:53], v[52:53], v[220:221], v[214:215]
	v_pk_fma_f32 v[50:51], v[50:51], v[218:219], v[212:213]
	v_pk_fma_f32 v[210:211], v[210:211], v[220:221], v[214:215]
	v_pk_fma_f32 v[208:209], v[208:209], v[218:219], v[212:213]
	v_cvt_pk_bf16_f32 v58, v58, v59
	v_cvt_pk_bf16_f32 v59, v56, v57
	v_cvt_pk_bf16_f32 v50, v50, v51
	v_cvt_pk_bf16_f32 v51, v52, v53
	v_cvt_pk_bf16_f32 v208, v208, v209
	v_cvt_pk_bf16_f32 v209, v210, v211
	global_store_dwordx2 v[102:103], v[58:59], off offset:3072
	global_store_dwordx2 v[104:105], v[50:51], off offset:3072
	global_store_dwordx2 v[106:107], v[208:209], off offset:3072
	s_nop 0
	s_waitcnt vmcnt(12)
	v_pk_mul_f32 v[30:31], v[30:31], v[222:223]
	v_pk_mul_f32 v[28:29], v[28:29], v[224:225]
	v_pk_add_f32 v[244:245], v[244:245], 1.0 op_sel_hi:[1,0]
	v_pk_add_f32 v[242:243], v[242:243], 1.0 op_sel_hi:[1,0]
	v_pk_fma_f32 v[28:29], v[28:29], v[244:245], v[228:229]
	v_pk_fma_f32 v[30:31], v[30:31], v[242:243], v[226:227]
	s_nop 0
	v_cvt_pk_bf16_f32 v30, v30, v31
	v_cvt_pk_bf16_f32 v31, v28, v29
	global_store_dwordx2 v[100:101], v[30:31], off offset:3584
	v_pk_mul_f32 v[28:29], v[54:55], v[32:33] op_sel_hi:[0,1]
	v_pk_mul_f32 v[30:31], v[54:55], v[34:35] op_sel_hi:[0,1]
	v_pk_mul_f32 v[30:31], v[30:31], v[222:223]
	v_pk_mul_f32 v[28:29], v[28:29], v[224:225]
	v_pk_fma_f32 v[30:31], v[30:31], v[242:243], v[226:227]
	v_pk_fma_f32 v[28:29], v[28:29], v[244:245], v[228:229]
	v_cvt_pk_bf16_f32 v30, v30, v31
	v_cvt_pk_bf16_f32 v31, v28, v29
	global_store_dwordx2 v[102:103], v[30:31], off offset:3584
	v_pk_mul_f32 v[28:29], v[64:65], v[36:37] op_sel_hi:[0,1]
	v_pk_mul_f32 v[30:31], v[64:65], v[38:39] op_sel_hi:[0,1]
	v_pk_mul_f32 v[30:31], v[30:31], v[222:223]
	v_pk_mul_f32 v[28:29], v[28:29], v[224:225]
	v_pk_fma_f32 v[30:31], v[30:31], v[242:243], v[226:227]
	v_pk_fma_f32 v[28:29], v[28:29], v[244:245], v[228:229]
	v_cvt_pk_bf16_f32 v30, v30, v31
	v_cvt_pk_bf16_f32 v31, v28, v29
	global_store_dwordx2 v[104:105], v[30:31], off offset:3584
	v_pk_mul_f32 v[28:29], v[66:67], v[40:41] op_sel_hi:[0,1]
	v_pk_mul_f32 v[30:31], v[66:67], v[42:43] op_sel_hi:[0,1]
	v_pk_mul_f32 v[222:223], v[30:31], v[222:223]
	v_pk_mul_f32 v[224:225], v[28:29], v[224:225]
	v_pk_fma_f32 v[222:223], v[222:223], v[242:243], v[226:227]
	v_pk_fma_f32 v[224:225], v[224:225], v[244:245], v[228:229]
	v_cvt_pk_bf16_f32 v222, v222, v223
	v_cvt_pk_bf16_f32 v223, v224, v225
	global_store_dwordx2 v[106:107], v[222:223], off offset:3584
	v_cndmask_b32_e64 v0, 0, 1, vcc
	v_cndmask_b32_e64 v1, 0, 1, s[18:19]
	v_cndmask_b32_e64 v0, v1, v0, s[2:3]
	v_and_b32_e32 v0, 1, v0
	v_cmp_eq_u32_e32 vcc, 1, v0
	s_cbranch_vccnz .LBB0_262

.LBB0_689:
	v_lshl_add_u64 v[0:1], s[16:17], 0, v[18:19]
	v_add_co_u32_e32 v0, vcc, 0x3000000, v0
	v_lshl_add_u64 v[36:37], s[12:13], 0, v[18:19]
	s_nop 0
	v_addc_co_u32_e32 v1, vcc, 0, v1, vcc
	global_load_dwordx2 v[2:3], v[0:1], off
	global_load_dwordx2 v[4:5], v[0:1], off offset:512
	global_load_dwordx2 v[6:7], v[0:1], off offset:1024
	global_load_dwordx2 v[28:29], v[0:1], off offset:1536
	global_load_dwordx2 v[30:31], v[0:1], off offset:2048
	global_load_dwordx2 v[32:33], v[0:1], off offset:2560
	global_load_dwordx2 v[34:35], v[0:1], off offset:3072
	s_nop 0
	global_load_dwordx2 v[0:1], v[0:1], off offset:3584
	v_add_co_u32_e32 v36, vcc, 0x3000000, v36
	s_add_i32 s18, s4, 2
	s_nop 0
	v_addc_co_u32_e32 v37, vcc, 0, v37, vcc
	global_load_dwordx2 v[38:39], v[36:37], off
	global_load_dwordx2 v[40:41], v[36:37], off offset:512
	global_load_dwordx2 v[42:43], v[36:37], off offset:1024
	global_load_dwordx2 v[46:47], v[36:37], off offset:1536
	global_load_dwordx2 v[48:49], v[36:37], off offset:2048
	global_load_dwordx2 v[50:51], v[36:37], off offset:2560
	global_load_dwordx2 v[52:53], v[36:37], off offset:3072
	s_nop 0
	global_load_dwordx2 v[36:37], v[36:37], off offset:3584
	s_ashr_i32 s19, s18, 31
	s_add_i32 s22, s4, 3
	s_lshl_b64 s[18:19], s[18:19], 12
	s_ashr_i32 s23, s22, 31
	v_lshl_add_u64 v[56:57], v[20:21], 0, s[18:19]
	s_lshl_b64 s[22:23], s[22:23], 12
	global_load_dwordx2 v[68:69], v[56:57], off
	global_load_dwordx2 v[70:71], v[56:57], off offset:512
	global_load_dwordx2 v[72:73], v[56:57], off offset:1024
	global_load_dwordx2 v[74:75], v[56:57], off offset:1536
	global_load_dwordx2 v[94:95], v[56:57], off offset:2048
	global_load_dwordx2 v[96:97], v[56:57], off offset:2560
	global_load_dwordx2 v[98:99], v[56:57], off offset:3072
	global_load_dwordx2 v[106:107], v[56:57], off offset:3584
	v_lshl_add_u64 v[56:57], v[20:21], 0, s[22:23]
	global_load_dwordx2 v[128:129], v[56:57], off
	global_load_dwordx2 v[130:131], v[56:57], off offset:512
	global_load_dwordx2 v[146:147], v[56:57], off offset:1024
	global_load_dwordx2 v[164:165], v[56:57], off offset:1536
	global_load_dwordx2 v[166:167], v[56:57], off offset:2048
	global_load_dwordx2 v[168:169], v[56:57], off offset:2560
	global_load_dwordx2 v[170:171], v[56:57], off offset:3072
	global_load_dwordx2 v[176:177], v[56:57], off offset:3584
	s_ashr_i32 s5, s4, 31
	s_lshr_b32 s5, s5, 20
	s_add_i32 s5, s4, s5
	s_ashr_i32 s5, s5, 12
	v_mad_i64_i32 v[230:231], vcc, s5, v237, v[22:23]
	v_mad_i64_i32 v[192:193], vcc, s5, v237, v[24:25]
	v_lshl_add_u64 v[250:251], v[230:231], 0, s[86:87]
	v_lshl_add_u64 v[252:253], v[192:193], 0, s[86:87]
	global_load_dwordx4 v[180:183], v[8:9], off
	global_load_dwordx4 v[184:187], v[230:231], off
	global_load_dwordx4 v[188:191], v[192:193], off
	global_load_dwordx4 v[196:199], v[8:9], off offset:1024
	global_load_dwordx4 v[200:203], v[230:231], off offset:1024
	global_load_dwordx4 v[204:207], v[192:193], off offset:1024
	global_load_dwordx4 v[208:211], v[8:9], off offset:2048
	global_load_dwordx4 v[212:215], v[230:231], off offset:2048
	global_load_dwordx4 v[218:221], v[192:193], off offset:2048
	global_load_dwordx4 v[222:225], v[8:9], off offset:3072
	global_load_dwordx4 v[226:229], v[230:231], off offset:3072
	global_load_dwordx4 v[242:245], v[192:193], off offset:3072
	s_add_i32 s4, s4, s6
	s_cmp_lt_i32 s4, s20
	s_waitcnt vmcnt(43)
	v_cvt_f32_f16_sdwa v163, v2 dst_sel:DWORD dst_unused:UNUSED_PAD src0_sel:WORD_1
	s_waitcnt vmcnt(42)
	v_cvt_f32_f16_sdwa v135, v4 dst_sel:DWORD dst_unused:UNUSED_PAD src0_sel:WORD_1
	v_cvt_f32_f16_sdwa v101, v3 dst_sel:DWORD dst_unused:UNUSED_PAD src0_sel:WORD_1
	v_cvt_f32_f16_e32 v162, v2
	v_cvt_f32_f16_sdwa v133, v5 dst_sel:DWORD dst_unused:UNUSED_PAD src0_sel:WORD_1
	v_cvt_f32_f16_e32 v134, v4
	v_cvt_f32_f16_e32 v100, v3
	v_cvt_f32_f16_e32 v132, v5
	s_waitcnt vmcnt(41)
	v_cvt_f32_f16_e32 v116, v6
	v_cvt_f32_f16_sdwa v117, v6 dst_sel:DWORD dst_unused:UNUSED_PAD src0_sel:WORD_1
	v_cvt_f32_f16_e32 v118, v7
	v_cvt_f32_f16_sdwa v119, v7 dst_sel:DWORD dst_unused:UNUSED_PAD src0_sel:WORD_1
	v_mov_b32_e32 v2, v163
	v_mov_b32_e32 v3, v135
	s_waitcnt vmcnt(40)
	v_cvt_f32_f16_e32 v108, v28
	v_cvt_f32_f16_sdwa v109, v28 dst_sel:DWORD dst_unused:UNUSED_PAD src0_sel:WORD_1
	v_cvt_f32_f16_e32 v110, v29
	v_cvt_f32_f16_sdwa v111, v29 dst_sel:DWORD dst_unused:UNUSED_PAD src0_sel:WORD_1
	s_waitcnt vmcnt(39)
	v_cvt_f32_f16_sdwa v87, v31 dst_sel:DWORD dst_unused:UNUSED_PAD src0_sel:WORD_1
	v_cvt_f32_f16_e32 v86, v31
	v_cvt_f32_f16_sdwa v85, v30 dst_sel:DWORD dst_unused:UNUSED_PAD src0_sel:WORD_1
	v_cvt_f32_f16_e32 v84, v30
	s_waitcnt vmcnt(36)
	v_cvt_f32_f16_sdwa v29, v1 dst_sel:DWORD dst_unused:UNUSED_PAD src0_sel:WORD_1
	v_cvt_f32_f16_e32 v28, v1
	v_cvt_f32_f16_sdwa v31, v0 dst_sel:DWORD dst_unused:UNUSED_PAD src0_sel:WORD_1
	v_cvt_f32_f16_e32 v30, v0
	v_mov_b32_e32 v0, v162
	v_mov_b32_e32 v1, v134
	v_pk_mul_f32 v[2:3], v[2:3], v[2:3]
	v_mov_b32_e32 v4, v101
	v_mov_b32_e32 v5, v133
	v_pk_fma_f32 v[0:1], v[0:1], v[0:1], v[2:3]
	v_mov_b32_e32 v2, v100
	v_mov_b32_e32 v3, v132
	v_pk_mul_f32 v[4:5], v[4:5], v[4:5]
	v_cvt_f32_f16_e32 v80, v32
	v_pk_fma_f32 v[2:3], v[2:3], v[2:3], v[4:5]
	v_pk_mul_f32 v[4:5], v[116:117], v[116:117]
	v_pk_add_f32 v[0:1], v[0:1], v[2:3]
	v_pk_mul_f32 v[2:3], v[118:119], v[118:119]
	v_pk_add_f32 v[0:1], v[0:1], v[0:1] op_sel:[0,1] op_sel_hi:[1,0]
	v_pk_mov_b32 v[6:7], v[4:5], v[2:3] op_sel:[1,0]
	v_mov_b32_e32 v5, v3
	v_pk_add_f32 v[2:3], v[6:7], v[4:5]
	v_mul_f32_e32 v4, v84, v84
	v_mul_f32_e32 v5, v85, v85
	v_pk_add_f32 v[2:3], v[2:3], v[2:3] op_sel:[0,1] op_sel_hi:[1,0]
	v_mov_b32_e32 v1, v4
	v_mov_b32_e32 v3, v5
	v_cvt_f32_f16_sdwa v81, v32 dst_sel:DWORD dst_unused:UNUSED_PAD src0_sel:WORD_1
	v_cvt_f32_f16_e32 v82, v33
	v_cvt_f32_f16_sdwa v83, v33 dst_sel:DWORD dst_unused:UNUSED_PAD src0_sel:WORD_1
	v_pk_add_f32 v[0:1], v[0:1], v[2:3]
	v_mul_f32_e32 v2, v109, v109
	v_mul_f32_e32 v4, v111, v111
	v_mul_f32_e32 v6, v86, v86
	v_mul_f32_e32 v7, v87, v87
	v_pk_fma_f32 v[2:3], v[108:109], v[108:109], v[2:3] op_sel_hi:[1,1,0]
	v_pk_fma_f32 v[4:5], v[110:111], v[110:111], v[4:5] op_sel_hi:[1,1,0]
	v_mov_b32_e32 v3, v6
	v_mov_b32_e32 v5, v7
	v_pk_add_f32 v[2:3], v[2:3], v[4:5]
	v_pk_mul_f32 v[4:5], v[80:81], v[80:81]
	v_pk_add_f32 v[0:1], v[0:1], v[2:3]
	v_pk_mul_f32 v[2:3], v[82:83], v[82:83]
	v_cvt_f32_f16_sdwa v57, v34 dst_sel:DWORD dst_unused:UNUSED_PAD src0_sel:WORD_1
	v_cvt_f32_f16_sdwa v59, v35 dst_sel:DWORD dst_unused:UNUSED_PAD src0_sel:WORD_1
	v_pk_mov_b32 v[6:7], v[4:5], v[2:3] op_sel:[1,0]
	v_mov_b32_e32 v5, v3
	v_cvt_f32_f16_e32 v56, v34
	v_cvt_f32_f16_e32 v58, v35
	v_pk_add_f32 v[2:3], v[6:7], v[4:5]
	v_mul_f32_e32 v4, v30, v30
	v_mul_f32_e32 v5, v31, v31
	v_pk_add_f32 v[0:1], v[0:1], v[0:1] op_sel:[0,1] op_sel_hi:[1,0]
	v_pk_add_f32 v[2:3], v[2:3], v[2:3] op_sel:[0,1] op_sel_hi:[1,0]
	v_mov_b32_e32 v1, v4
	v_mov_b32_e32 v3, v5
	v_pk_add_f32 v[0:1], v[0:1], v[2:3]
	v_mul_f32_e32 v2, v57, v57
	v_mul_f32_e32 v4, v59, v59
	v_mul_f32_e32 v6, v28, v28
	v_mul_f32_e32 v7, v29, v29
	v_pk_fma_f32 v[2:3], v[56:57], v[56:57], v[2:3] op_sel_hi:[1,1,0]
	v_pk_fma_f32 v[4:5], v[58:59], v[58:59], v[4:5] op_sel_hi:[1,1,0]
	v_mov_b32_e32 v3, v6
	v_mov_b32_e32 v5, v7
	v_pk_add_f32 v[2:3], v[2:3], v[4:5]
	s_waitcnt vmcnt(35)
	v_cvt_f32_f16_sdwa v161, v38 dst_sel:DWORD dst_unused:UNUSED_PAD src0_sel:WORD_1
	v_pk_add_f32 v[0:1], v[0:1], v[2:3]
	s_waitcnt vmcnt(34)
	v_cvt_f32_f16_sdwa v143, v40 dst_sel:DWORD dst_unused:UNUSED_PAD src0_sel:WORD_1
	v_add_f32_e32 v0, v0, v1
	v_cvt_f32_f16_sdwa v103, v39 dst_sel:DWORD dst_unused:UNUSED_PAD src0_sel:WORD_1
	v_cvt_f32_f16_e32 v160, v38
	v_cvt_f32_f16_sdwa v141, v41 dst_sel:DWORD dst_unused:UNUSED_PAD src0_sel:WORD_1
	v_cvt_f32_f16_e32 v142, v40
	s_waitcnt lgkmcnt(0)
	s_nop 1
	v_add_f32_dpp v0, v0, v0 quad_perm:[1,0,3,2] row_mask:0xf bank_mask:0xf
	v_cvt_f32_f16_e32 v102, v39
	v_cvt_f32_f16_e32 v140, v41
	s_waitcnt vmcnt(33)
	v_cvt_f32_f16_e32 v124, v42
	v_cvt_f32_f16_sdwa v125, v42 dst_sel:DWORD dst_unused:UNUSED_PAD src0_sel:WORD_1
	s_waitcnt lgkmcnt(0)
	s_nop 1
	v_add_f32_dpp v0, v0, v0 quad_perm:[2,3,0,1] row_mask:0xf bank_mask:0xf
	v_cvt_f32_f16_e32 v126, v43
	v_cvt_f32_f16_sdwa v127, v43 dst_sel:DWORD dst_unused:UNUSED_PAD src0_sel:WORD_1
	v_mov_b32_e32 v2, v161
	v_mov_b32_e32 v3, v143
	s_waitcnt lgkmcnt(0)
	s_nop 1
	v_add_f32_dpp v0, v0, v0 row_half_mirror row_mask:0xf bank_mask:0xf
	v_pk_mul_f32 v[2:3], v[2:3], v[2:3]
	v_mov_b32_e32 v4, v103
	v_mov_b32_e32 v5, v141
	v_pk_mul_f32 v[4:5], v[4:5], v[4:5]
	s_waitcnt lgkmcnt(0)
	s_nop 1
	v_add_f32_dpp v0, v0, v0 row_mirror row_mask:0xf bank_mask:0xf
	s_waitcnt vmcnt(31)
	v_cvt_f32_f16_sdwa v91, v48 dst_sel:DWORD dst_unused:UNUSED_PAD src0_sel:WORD_1
	v_cvt_f32_f16_e32 v90, v48
	v_cvt_f32_f16_sdwa v113, v46 dst_sel:DWORD dst_unused:UNUSED_PAD src0_sel:WORD_1
	v_cvt_f32_f16_sdwa v115, v47 dst_sel:DWORD dst_unused:UNUSED_PAD src0_sel:WORD_1
	s_waitcnt lgkmcnt(0)
	v_mov_b32_e32 v1, v0
	s_nop 1
	v_permlane16_swap_b32_e32 v0, v1
	s_nop 0
	v_add_f32_e32 v0, v0, v1
	v_cvt_f32_f16_e32 v112, v46
	v_cvt_f32_f16_e32 v114, v47
	v_cvt_f32_f16_sdwa v89, v49 dst_sel:DWORD dst_unused:UNUSED_PAD src0_sel:WORD_1
	v_cvt_f32_f16_e32 v88, v49
	s_waitcnt lgkmcnt(0)
	v_mov_b32_e32 v1, v0
	s_nop 1
	v_permlane32_swap_b32_e32 v0, v1
	s_nop 0
	v_add_f32_e32 v0, v0, v1
	v_fmamk_f32 v0, v0, 0x3a000000, v232
	v_rsq_f32_e32 v44, v0
	v_mov_b32_e32 v0, v160
	v_mov_b32_e32 v1, v142
	v_pk_fma_f32 v[0:1], v[0:1], v[0:1], v[2:3]
	v_mov_b32_e32 v2, v102
	v_mov_b32_e32 v3, v140
	v_pk_fma_f32 v[2:3], v[2:3], v[2:3], v[4:5]
	v_pk_mul_f32 v[4:5], v[124:125], v[124:125]
	v_pk_add_f32 v[0:1], v[0:1], v[2:3]
	v_pk_mul_f32 v[2:3], v[126:127], v[126:127]
	v_pk_add_f32 v[0:1], v[0:1], v[0:1] op_sel:[0,1] op_sel_hi:[1,0]
	v_pk_mov_b32 v[6:7], v[4:5], v[2:3] op_sel:[1,0]
	v_mov_b32_e32 v5, v3
	v_pk_add_f32 v[2:3], v[6:7], v[4:5]
	v_mul_f32_e32 v4, v90, v90
	v_mul_f32_e32 v5, v91, v91
	v_pk_add_f32 v[2:3], v[2:3], v[2:3] op_sel:[0,1] op_sel_hi:[1,0]
	v_mov_b32_e32 v1, v4
	v_mov_b32_e32 v3, v5
	s_waitcnt vmcnt(30)
	v_cvt_f32_f16_e32 v76, v50
	v_cvt_f32_f16_sdwa v77, v50 dst_sel:DWORD dst_unused:UNUSED_PAD src0_sel:WORD_1
	v_cvt_f32_f16_e32 v78, v51
	v_cvt_f32_f16_sdwa v79, v51 dst_sel:DWORD dst_unused:UNUSED_PAD src0_sel:WORD_1
	v_pk_add_f32 v[0:1], v[0:1], v[2:3]
	v_mul_f32_e32 v2, v113, v113
	v_mul_f32_e32 v4, v115, v115
	v_mul_f32_e32 v6, v88, v88
	v_mul_f32_e32 v7, v89, v89
	v_pk_fma_f32 v[2:3], v[112:113], v[112:113], v[2:3] op_sel_hi:[1,1,0]
	v_pk_fma_f32 v[4:5], v[114:115], v[114:115], v[4:5] op_sel_hi:[1,1,0]
	v_mov_b32_e32 v3, v6
	v_mov_b32_e32 v5, v7
	s_waitcnt vmcnt(28)
	v_cvt_f32_f16_sdwa v35, v36 dst_sel:DWORD dst_unused:UNUSED_PAD src0_sel:WORD_1
	v_cvt_f32_f16_e32 v34, v36
	v_pk_add_f32 v[2:3], v[2:3], v[4:5]
	v_pk_mul_f32 v[4:5], v[76:77], v[76:77]
	v_pk_add_f32 v[0:1], v[0:1], v[2:3]
	v_pk_mul_f32 v[2:3], v[78:79], v[78:79]
	v_cvt_f32_f16_sdwa v61, v52 dst_sel:DWORD dst_unused:UNUSED_PAD src0_sel:WORD_1
	v_cvt_f32_f16_sdwa v63, v53 dst_sel:DWORD dst_unused:UNUSED_PAD src0_sel:WORD_1
	v_pk_mov_b32 v[6:7], v[4:5], v[2:3] op_sel:[1,0]
	v_mov_b32_e32 v5, v3
	v_cvt_f32_f16_e32 v60, v52
	v_cvt_f32_f16_e32 v62, v53
	v_cvt_f32_f16_sdwa v33, v37 dst_sel:DWORD dst_unused:UNUSED_PAD src0_sel:WORD_1
	v_cvt_f32_f16_e32 v32, v37
	v_pk_add_f32 v[2:3], v[6:7], v[4:5]
	v_mul_f32_e32 v4, v34, v34
	v_mul_f32_e32 v5, v35, v35
	v_pk_add_f32 v[0:1], v[0:1], v[0:1] op_sel:[0,1] op_sel_hi:[1,0]
	v_pk_add_f32 v[2:3], v[2:3], v[2:3] op_sel:[0,1] op_sel_hi:[1,0]
	v_mov_b32_e32 v1, v4
	v_mov_b32_e32 v3, v5
	v_pk_add_f32 v[0:1], v[0:1], v[2:3]
	v_mul_f32_e32 v2, v61, v61
	v_mul_f32_e32 v4, v63, v63
	v_mul_f32_e32 v6, v32, v32
	v_mul_f32_e32 v7, v33, v33
	v_pk_fma_f32 v[2:3], v[60:61], v[60:61], v[2:3] op_sel_hi:[1,1,0]
	v_pk_fma_f32 v[4:5], v[62:63], v[62:63], v[4:5] op_sel_hi:[1,1,0]
	v_mov_b32_e32 v3, v6
	v_mov_b32_e32 v5, v7
	v_pk_add_f32 v[2:3], v[2:3], v[4:5]
	s_waitcnt vmcnt(27)
	v_cvt_f32_f16_sdwa v159, v68 dst_sel:DWORD dst_unused:UNUSED_PAD src0_sel:WORD_1
	v_pk_add_f32 v[0:1], v[0:1], v[2:3]
	s_waitcnt vmcnt(26)
	v_cvt_f32_f16_sdwa v151, v70 dst_sel:DWORD dst_unused:UNUSED_PAD src0_sel:WORD_1
	v_add_f32_e32 v0, v0, v1
	v_cvt_f32_f16_sdwa v105, v69 dst_sel:DWORD dst_unused:UNUSED_PAD src0_sel:WORD_1
	v_cvt_f32_f16_e32 v158, v68
	v_cvt_f32_f16_sdwa v149, v71 dst_sel:DWORD dst_unused:UNUSED_PAD src0_sel:WORD_1
	v_cvt_f32_f16_e32 v150, v70
	s_waitcnt lgkmcnt(0)
	s_nop 1
	v_add_f32_dpp v0, v0, v0 quad_perm:[1,0,3,2] row_mask:0xf bank_mask:0xf
	v_cvt_f32_f16_e32 v104, v69
	v_cvt_f32_f16_e32 v148, v71
	s_waitcnt vmcnt(25)
	v_cvt_f32_f16_e32 v136, v72
	v_cvt_f32_f16_sdwa v137, v72 dst_sel:DWORD dst_unused:UNUSED_PAD src0_sel:WORD_1
	s_waitcnt lgkmcnt(0)
	s_nop 1
	v_add_f32_dpp v0, v0, v0 quad_perm:[2,3,0,1] row_mask:0xf bank_mask:0xf
	v_cvt_f32_f16_e32 v138, v73
	v_cvt_f32_f16_sdwa v139, v73 dst_sel:DWORD dst_unused:UNUSED_PAD src0_sel:WORD_1
	v_mov_b32_e32 v2, v159
	v_mov_b32_e32 v3, v151
	s_waitcnt lgkmcnt(0)
	s_nop 1
	v_add_f32_dpp v0, v0, v0 row_half_mirror row_mask:0xf bank_mask:0xf
	v_pk_mul_f32 v[2:3], v[2:3], v[2:3]
	v_mov_b32_e32 v4, v105
	v_mov_b32_e32 v5, v149
	v_pk_mul_f32 v[4:5], v[4:5], v[4:5]
	s_waitcnt lgkmcnt(0)
	s_nop 1
	v_add_f32_dpp v0, v0, v0 row_mirror row_mask:0xf bank_mask:0xf
	s_waitcnt vmcnt(23)
	v_cvt_f32_f16_sdwa v93, v95 dst_sel:DWORD dst_unused:UNUSED_PAD src0_sel:WORD_1
	v_cvt_f32_f16_e32 v92, v95
	v_cvt_f32_f16_sdwa v95, v94 dst_sel:DWORD dst_unused:UNUSED_PAD src0_sel:WORD_1
	v_cvt_f32_f16_e32 v94, v94
	s_waitcnt lgkmcnt(0)
	v_mov_b32_e32 v1, v0
	s_nop 1
	v_permlane16_swap_b32_e32 v0, v1
	s_nop 0
	v_add_f32_e32 v0, v0, v1
	v_cvt_f32_f16_sdwa v121, v74 dst_sel:DWORD dst_unused:UNUSED_PAD src0_sel:WORD_1
	v_cvt_f32_f16_sdwa v123, v75 dst_sel:DWORD dst_unused:UNUSED_PAD src0_sel:WORD_1
	v_cvt_f32_f16_e32 v120, v74
	v_cvt_f32_f16_e32 v122, v75
	s_waitcnt lgkmcnt(0)
	v_mov_b32_e32 v1, v0
	s_nop 1
	v_permlane32_swap_b32_e32 v0, v1
	s_nop 0
	v_add_f32_e32 v0, v0, v1
	v_fmamk_f32 v0, v0, 0x3a000000, v232
	v_rsq_f32_e32 v54, v0
	v_mov_b32_e32 v0, v158
	v_mov_b32_e32 v1, v150
	v_pk_fma_f32 v[0:1], v[0:1], v[0:1], v[2:3]
	v_mov_b32_e32 v2, v104
	v_mov_b32_e32 v3, v148
	v_pk_fma_f32 v[2:3], v[2:3], v[2:3], v[4:5]
	v_pk_mul_f32 v[4:5], v[136:137], v[136:137]
	v_pk_add_f32 v[0:1], v[0:1], v[2:3]
	v_pk_mul_f32 v[2:3], v[138:139], v[138:139]
	v_pk_add_f32 v[0:1], v[0:1], v[0:1] op_sel:[0,1] op_sel_hi:[1,0]
	v_pk_mov_b32 v[6:7], v[4:5], v[2:3] op_sel:[1,0]
	v_mov_b32_e32 v5, v3
	v_pk_add_f32 v[2:3], v[6:7], v[4:5]
	v_mul_f32_e32 v4, v94, v94
	v_mul_f32_e32 v5, v95, v95
	v_pk_add_f32 v[2:3], v[2:3], v[2:3] op_sel:[0,1] op_sel_hi:[1,0]
	v_mov_b32_e32 v1, v4
	v_mov_b32_e32 v3, v5
	s_waitcnt vmcnt(22)
	v_cvt_f32_f16_e32 v72, v96
	v_cvt_f32_f16_sdwa v73, v96 dst_sel:DWORD dst_unused:UNUSED_PAD src0_sel:WORD_1
	v_cvt_f32_f16_e32 v74, v97
	v_cvt_f32_f16_sdwa v75, v97 dst_sel:DWORD dst_unused:UNUSED_PAD src0_sel:WORD_1
	v_pk_add_f32 v[0:1], v[0:1], v[2:3]
	v_mul_f32_e32 v2, v121, v121
	v_mul_f32_e32 v4, v123, v123
	v_mul_f32_e32 v6, v92, v92
	v_mul_f32_e32 v7, v93, v93
	v_pk_fma_f32 v[2:3], v[120:121], v[120:121], v[2:3] op_sel_hi:[1,1,0]
	v_pk_fma_f32 v[4:5], v[122:123], v[122:123], v[4:5] op_sel_hi:[1,1,0]
	v_mov_b32_e32 v3, v6
	v_mov_b32_e32 v5, v7
	s_waitcnt vmcnt(20)
	v_cvt_f32_f16_sdwa v39, v106 dst_sel:DWORD dst_unused:UNUSED_PAD src0_sel:WORD_1
	v_cvt_f32_f16_e32 v38, v106
	v_pk_add_f32 v[2:3], v[2:3], v[4:5]
	v_pk_mul_f32 v[4:5], v[72:73], v[72:73]
	v_pk_add_f32 v[0:1], v[0:1], v[2:3]
	v_pk_mul_f32 v[2:3], v[74:75], v[74:75]
	v_cvt_f32_f16_sdwa v51, v98 dst_sel:DWORD dst_unused:UNUSED_PAD src0_sel:WORD_1
	v_cvt_f32_f16_sdwa v53, v99 dst_sel:DWORD dst_unused:UNUSED_PAD src0_sel:WORD_1
	v_pk_mov_b32 v[6:7], v[4:5], v[2:3] op_sel:[1,0]
	v_mov_b32_e32 v5, v3
	v_cvt_f32_f16_e32 v50, v98
	v_cvt_f32_f16_e32 v52, v99
	v_cvt_f32_f16_sdwa v37, v107 dst_sel:DWORD dst_unused:UNUSED_PAD src0_sel:WORD_1
	v_cvt_f32_f16_e32 v36, v107
	v_pk_add_f32 v[2:3], v[6:7], v[4:5]
	v_mul_f32_e32 v4, v38, v38
	v_mul_f32_e32 v5, v39, v39
	v_pk_add_f32 v[0:1], v[0:1], v[0:1] op_sel:[0,1] op_sel_hi:[1,0]
	v_pk_add_f32 v[2:3], v[2:3], v[2:3] op_sel:[0,1] op_sel_hi:[1,0]
	v_mov_b32_e32 v1, v4
	v_mov_b32_e32 v3, v5
	v_pk_add_f32 v[0:1], v[0:1], v[2:3]
	v_mul_f32_e32 v2, v51, v51
	v_mul_f32_e32 v4, v53, v53
	v_mul_f32_e32 v6, v36, v36
	v_mul_f32_e32 v7, v37, v37
	v_pk_fma_f32 v[2:3], v[50:51], v[50:51], v[2:3] op_sel_hi:[1,1,0]
	v_pk_fma_f32 v[4:5], v[52:53], v[52:53], v[4:5] op_sel_hi:[1,1,0]
	v_mov_b32_e32 v3, v6
	v_mov_b32_e32 v5, v7
	v_pk_add_f32 v[2:3], v[2:3], v[4:5]
	s_waitcnt vmcnt(19)
	v_cvt_f32_f16_sdwa v157, v128 dst_sel:DWORD dst_unused:UNUSED_PAD src0_sel:WORD_1
	v_pk_add_f32 v[0:1], v[0:1], v[2:3]
	s_waitcnt vmcnt(18)
	v_cvt_f32_f16_sdwa v155, v130 dst_sel:DWORD dst_unused:UNUSED_PAD src0_sel:WORD_1
	v_add_f32_e32 v0, v0, v1
	v_cvt_f32_f16_sdwa v107, v129 dst_sel:DWORD dst_unused:UNUSED_PAD src0_sel:WORD_1
	v_cvt_f32_f16_e32 v156, v128
	v_cvt_f32_f16_sdwa v153, v131 dst_sel:DWORD dst_unused:UNUSED_PAD src0_sel:WORD_1
	v_cvt_f32_f16_e32 v154, v130
	s_waitcnt lgkmcnt(0)
	s_nop 1
	v_add_f32_dpp v0, v0, v0 quad_perm:[1,0,3,2] row_mask:0xf bank_mask:0xf
	v_cvt_f32_f16_e32 v106, v129
	v_cvt_f32_f16_e32 v152, v131
	s_waitcnt vmcnt(17)
	v_cvt_f32_f16_e32 v144, v146
	v_cvt_f32_f16_sdwa v145, v146 dst_sel:DWORD dst_unused:UNUSED_PAD src0_sel:WORD_1
	s_waitcnt lgkmcnt(0)
	s_nop 1
	v_add_f32_dpp v0, v0, v0 quad_perm:[2,3,0,1] row_mask:0xf bank_mask:0xf
	v_cvt_f32_f16_e32 v146, v147
	v_cvt_f32_f16_sdwa v147, v147 dst_sel:DWORD dst_unused:UNUSED_PAD src0_sel:WORD_1
	v_mov_b32_e32 v2, v157
	v_mov_b32_e32 v3, v155
	s_waitcnt lgkmcnt(0)
	s_nop 1
	v_add_f32_dpp v0, v0, v0 row_half_mirror row_mask:0xf bank_mask:0xf
	v_pk_mul_f32 v[2:3], v[2:3], v[2:3]
	v_mov_b32_e32 v4, v107
	v_mov_b32_e32 v5, v153
	v_pk_mul_f32 v[4:5], v[4:5], v[4:5]
	s_waitcnt lgkmcnt(0)
	s_nop 1
	v_add_f32_dpp v0, v0, v0 row_mirror row_mask:0xf bank_mask:0xf
	s_waitcnt vmcnt(15)
	v_cvt_f32_f16_sdwa v99, v166 dst_sel:DWORD dst_unused:UNUSED_PAD src0_sel:WORD_1
	v_cvt_f32_f16_e32 v98, v166
	v_cvt_f32_f16_sdwa v129, v164 dst_sel:DWORD dst_unused:UNUSED_PAD src0_sel:WORD_1
	v_cvt_f32_f16_sdwa v131, v165 dst_sel:DWORD dst_unused:UNUSED_PAD src0_sel:WORD_1
	s_waitcnt lgkmcnt(0)
	v_mov_b32_e32 v1, v0
	s_nop 1
	v_permlane16_swap_b32_e32 v0, v1
	s_nop 0
	v_add_f32_e32 v0, v0, v1
	v_cvt_f32_f16_e32 v128, v164
	v_cvt_f32_f16_e32 v130, v165
	v_cvt_f32_f16_sdwa v97, v167 dst_sel:DWORD dst_unused:UNUSED_PAD src0_sel:WORD_1
	v_cvt_f32_f16_e32 v96, v167
	s_waitcnt lgkmcnt(0)
	v_mov_b32_e32 v1, v0
	s_nop 1
	v_permlane32_swap_b32_e32 v0, v1
	s_nop 0
	v_add_f32_e32 v0, v0, v1
	v_fmamk_f32 v0, v0, 0x3a000000, v232
	v_rsq_f32_e32 v64, v0
	v_mov_b32_e32 v0, v156
	v_mov_b32_e32 v1, v154
	v_pk_fma_f32 v[0:1], v[0:1], v[0:1], v[2:3]
	v_mov_b32_e32 v2, v106
	v_mov_b32_e32 v3, v152
	v_pk_fma_f32 v[2:3], v[2:3], v[2:3], v[4:5]
	v_pk_mul_f32 v[4:5], v[144:145], v[144:145]
	v_pk_add_f32 v[0:1], v[0:1], v[2:3]
	v_pk_mul_f32 v[2:3], v[146:147], v[146:147]
	v_pk_add_f32 v[0:1], v[0:1], v[0:1] op_sel:[0,1] op_sel_hi:[1,0]
	v_pk_mov_b32 v[6:7], v[4:5], v[2:3] op_sel:[1,0]
	v_mov_b32_e32 v5, v3
	v_pk_add_f32 v[2:3], v[6:7], v[4:5]
	v_mul_f32_e32 v4, v98, v98
	v_mul_f32_e32 v5, v99, v99
	v_pk_add_f32 v[2:3], v[2:3], v[2:3] op_sel:[0,1] op_sel_hi:[1,0]
	v_mov_b32_e32 v1, v4
	v_mov_b32_e32 v3, v5
	s_waitcnt vmcnt(14)
	v_cvt_f32_f16_e32 v68, v168
	v_cvt_f32_f16_sdwa v69, v168 dst_sel:DWORD dst_unused:UNUSED_PAD src0_sel:WORD_1
	v_cvt_f32_f16_e32 v70, v169
	v_cvt_f32_f16_sdwa v71, v169 dst_sel:DWORD dst_unused:UNUSED_PAD src0_sel:WORD_1
	v_pk_add_f32 v[0:1], v[0:1], v[2:3]
	v_mul_f32_e32 v2, v129, v129
	v_mul_f32_e32 v4, v131, v131
	v_mul_f32_e32 v6, v96, v96
	v_mul_f32_e32 v7, v97, v97
	v_pk_fma_f32 v[2:3], v[128:129], v[128:129], v[2:3] op_sel_hi:[1,1,0]
	v_pk_fma_f32 v[4:5], v[130:131], v[130:131], v[4:5] op_sel_hi:[1,1,0]
	v_mov_b32_e32 v3, v6
	v_mov_b32_e32 v5, v7
	s_waitcnt vmcnt(12)
	v_cvt_f32_f16_sdwa v43, v176 dst_sel:DWORD dst_unused:UNUSED_PAD src0_sel:WORD_1
	v_cvt_f32_f16_e32 v42, v176
	v_pk_add_f32 v[2:3], v[2:3], v[4:5]
	v_pk_mul_f32 v[4:5], v[68:69], v[68:69]
	v_pk_add_f32 v[0:1], v[0:1], v[2:3]
	v_pk_mul_f32 v[2:3], v[70:71], v[70:71]
	v_cvt_f32_f16_sdwa v47, v170 dst_sel:DWORD dst_unused:UNUSED_PAD src0_sel:WORD_1
	v_cvt_f32_f16_sdwa v49, v171 dst_sel:DWORD dst_unused:UNUSED_PAD src0_sel:WORD_1
	v_pk_mov_b32 v[6:7], v[4:5], v[2:3] op_sel:[1,0]
	v_mov_b32_e32 v5, v3
	v_cvt_f32_f16_e32 v46, v170
	v_cvt_f32_f16_e32 v48, v171
	v_cvt_f32_f16_sdwa v41, v177 dst_sel:DWORD dst_unused:UNUSED_PAD src0_sel:WORD_1
	v_cvt_f32_f16_e32 v40, v177
	v_pk_add_f32 v[2:3], v[6:7], v[4:5]
	v_mul_f32_e32 v4, v42, v42
	v_mul_f32_e32 v5, v43, v43
	v_pk_add_f32 v[0:1], v[0:1], v[0:1] op_sel:[0,1] op_sel_hi:[1,0]
	v_pk_add_f32 v[2:3], v[2:3], v[2:3] op_sel:[0,1] op_sel_hi:[1,0]
	v_mov_b32_e32 v1, v4
	v_mov_b32_e32 v3, v5
	v_pk_add_f32 v[0:1], v[0:1], v[2:3]
	v_mul_f32_e32 v2, v47, v47
	v_mul_f32_e32 v4, v49, v49
	v_mul_f32_e32 v6, v40, v40
	v_mul_f32_e32 v7, v41, v41
	v_pk_fma_f32 v[2:3], v[46:47], v[46:47], v[2:3] op_sel_hi:[1,1,0]
	v_pk_fma_f32 v[4:5], v[48:49], v[48:49], v[4:5] op_sel_hi:[1,1,0]
	v_mov_b32_e32 v3, v6
	v_mov_b32_e32 v5, v7
	v_pk_add_f32 v[2:3], v[2:3], v[4:5]
	v_mad_i64_i32 v[166:167], s[52:53], s5, v237, v[22:23]
	v_pk_add_f32 v[0:1], v[0:1], v[2:3]
	v_mad_i64_i32 v[164:165], s[52:53], s5, v237, v[24:25]
	v_add_f32_e32 v0, v0, v1
	v_pk_mul_f32 v[100:101], v[44:45], v[100:101] op_sel_hi:[0,1]
	v_pk_mul_f32 v[162:163], v[44:45], v[162:163] op_sel_hi:[0,1]
	v_pk_mul_f32 v[102:103], v[54:55], v[102:103] op_sel_hi:[0,1]
	v_pk_mul_f32 v[160:161], v[54:55], v[160:161] op_sel_hi:[0,1]
	s_waitcnt lgkmcnt(0)
	s_nop 1
	v_add_f32_dpp v0, v0, v0 quad_perm:[1,0,3,2] row_mask:0xf bank_mask:0xf
	v_pk_mul_f32 v[104:105], v[64:65], v[104:105] op_sel_hi:[0,1]
	v_pk_mul_f32 v[158:159], v[64:65], v[158:159] op_sel_hi:[0,1]
	v_pk_mul_f32 v[132:133], v[44:45], v[132:133] op_sel_hi:[0,1]
	v_pk_mul_f32 v[134:135], v[44:45], v[134:135] op_sel_hi:[0,1]
	s_waitcnt lgkmcnt(0)
	s_nop 1
	v_add_f32_dpp v0, v0, v0 quad_perm:[2,3,0,1] row_mask:0xf bank_mask:0xf
	v_pk_mul_f32 v[118:119], v[44:45], v[118:119] op_sel_hi:[0,1]
	v_pk_mul_f32 v[116:117], v[44:45], v[116:117] op_sel_hi:[0,1]
	v_pk_mul_f32 v[110:111], v[44:45], v[110:111] op_sel_hi:[0,1]
	v_pk_mul_f32 v[108:109], v[44:45], v[108:109] op_sel_hi:[0,1]
	s_waitcnt lgkmcnt(0)
	s_nop 1
	v_add_f32_dpp v0, v0, v0 row_half_mirror row_mask:0xf bank_mask:0xf
	v_pk_mul_f32 v[86:87], v[44:45], v[86:87] op_sel_hi:[0,1]
	v_pk_mul_f32 v[84:85], v[44:45], v[84:85] op_sel_hi:[0,1]
	v_pk_mul_f32 v[82:83], v[44:45], v[82:83] op_sel_hi:[0,1]
	v_pk_mul_f32 v[80:81], v[44:45], v[80:81] op_sel_hi:[0,1]
	s_waitcnt lgkmcnt(0)
	s_nop 1
	v_add_f32_dpp v0, v0, v0 row_mirror row_mask:0xf bank_mask:0xf
	v_pk_mul_f32 v[78:79], v[54:55], v[78:79] op_sel_hi:[0,1]
	v_pk_mul_f32 v[76:77], v[54:55], v[76:77] op_sel_hi:[0,1]
	v_pk_mul_f32 v[74:75], v[64:65], v[74:75] op_sel_hi:[0,1]
	v_pk_mul_f32 v[72:73], v[64:65], v[72:73] op_sel_hi:[0,1]
	s_waitcnt lgkmcnt(0)
	v_mov_b32_e32 v1, v0
	s_nop 1
	v_permlane16_swap_b32_e32 v0, v1
	s_nop 0
	v_add_f32_e32 v0, v0, v1
	v_pk_mul_f32 v[58:59], v[44:45], v[58:59] op_sel_hi:[0,1]
	v_pk_mul_f32 v[56:57], v[44:45], v[56:57] op_sel_hi:[0,1]
	v_pk_mul_f32 v[52:53], v[64:65], v[52:53] op_sel_hi:[0,1]
	v_pk_mul_f32 v[50:51], v[64:65], v[50:51] op_sel_hi:[0,1]
	s_waitcnt lgkmcnt(0)
	v_mov_b32_e32 v1, v0
	s_nop 1
	v_permlane32_swap_b32_e32 v0, v1
	s_nop 0
	v_add_f32_e32 v0, v0, v1
	v_fmamk_f32 v0, v0, 0x3a000000, v232
	v_rsq_f32_e32 v66, v0
	v_pk_mul_f32 v[28:29], v[44:45], v[28:29] op_sel_hi:[0,1]
	v_pk_mul_f32 v[30:31], v[44:45], v[30:31] op_sel_hi:[0,1]
	v_pk_mul_f32 v[106:107], v[66:67], v[106:107] op_sel_hi:[0,1]
	v_pk_mul_f32 v[156:157], v[66:67], v[156:157] op_sel_hi:[0,1]
	v_pk_mul_f32 v[70:71], v[66:67], v[70:71] op_sel_hi:[0,1]
	v_pk_mul_f32 v[68:69], v[66:67], v[68:69] op_sel_hi:[0,1]
	v_pk_mul_f32 v[48:49], v[66:67], v[48:49] op_sel_hi:[0,1]
	v_pk_mul_f32 v[46:47], v[66:67], v[46:47] op_sel_hi:[0,1]
	s_waitcnt vmcnt(9)
	v_pk_mul_f32 v[162:163], v[162:163], v[180:181]
	v_pk_mul_f32 v[100:101], v[100:101], v[182:183]
	v_pk_add_f32 v[168:169], v[190:191], 1.0 op_sel_hi:[1,0]
	v_pk_add_f32 v[170:171], v[188:189], 1.0 op_sel_hi:[1,0]
	v_pk_fma_f32 v[100:101], v[100:101], v[168:169], v[186:187]
	v_pk_fma_f32 v[162:163], v[162:163], v[170:171], v[184:185]
	v_pk_mul_f32 v[160:161], v[160:161], v[180:181]
	v_cvt_pk_bf16_f32 v162, v162, v163
	v_cvt_pk_bf16_f32 v163, v100, v101
	v_lshl_add_u64 v[100:101], s[14:15], 0, v[18:19]
	v_pk_mul_f32 v[102:103], v[102:103], v[182:183]
	v_add_co_u32_e32 v100, vcc, s30, v100
	v_pk_fma_f32 v[102:103], v[102:103], v[168:169], v[186:187]
	v_pk_fma_f32 v[160:161], v[160:161], v[170:171], v[184:185]
	v_addc_co_u32_e32 v101, vcc, 0, v101, vcc
	v_cvt_pk_bf16_f32 v160, v160, v161
	v_cvt_pk_bf16_f32 v161, v102, v103
	v_lshl_add_u64 v[102:103], s[8:9], 0, v[18:19]
	v_pk_mul_f32 v[158:159], v[180:181], v[158:159]
	v_pk_mul_f32 v[104:105], v[182:183], v[104:105]
	v_pk_mul_f32 v[180:181], v[180:181], v[156:157]
	v_pk_mul_f32 v[182:183], v[182:183], v[106:107]
	v_add_co_u32_e32 v102, vcc, s30, v102
	v_pk_fma_f32 v[104:105], v[104:105], v[168:169], v[186:187]
	v_pk_fma_f32 v[158:159], v[158:159], v[170:171], v[184:185]
	v_pk_fma_f32 v[186:187], v[168:169], v[182:183], v[186:187]
	v_pk_fma_f32 v[184:185], v[170:171], v[180:181], v[184:185]
	v_addc_co_u32_e32 v103, vcc, 0, v103, vcc
	v_cvt_pk_bf16_f32 v158, v158, v159
	v_cvt_pk_bf16_f32 v159, v104, v105
	v_lshl_add_u64 v[104:105], v[26:27], 0, s[18:19]
	v_cvt_pk_bf16_f32 v184, v184, v185
	v_cvt_pk_bf16_f32 v185, v186, v187
	v_lshl_add_u64 v[106:107], v[26:27], 0, s[22:23]
	global_store_dwordx2 v[100:101], v[162:163], off
	global_store_dwordx2 v[102:103], v[160:161], off
	global_store_dwordx2 v[104:105], v[158:159], off
	global_store_dwordx2 v[106:107], v[184:185], off
	global_load_dwordx4 v[180:183], v[10:11], off
	global_load_dwordx4 v[184:187], v[252:253], off
	global_load_dwordx4 v[188:191], v[250:251], off
	s_nop 0
	s_cselect_b64 s[18:19], -1, 0
	s_add_u32 s8, s8, s10
	s_addc_u32 s9, s9, s11
	s_add_u32 s12, s12, s10
	s_addc_u32 s13, s13, s11
	s_add_u32 s14, s14, s10
	s_addc_u32 s15, s15, s11
	s_add_u32 s16, s16, s10
	s_addc_u32 s17, s17, s11
	s_waitcnt vmcnt(13)
	v_pk_mul_f32 v[134:135], v[134:135], v[196:197]
	v_pk_mul_f32 v[132:133], v[132:133], v[198:199]
	v_pk_add_f32 v[206:207], v[206:207], 1.0 op_sel_hi:[1,0]
	v_pk_add_f32 v[204:205], v[204:205], 1.0 op_sel_hi:[1,0]
	v_pk_fma_f32 v[132:133], v[132:133], v[206:207], v[202:203]
	v_pk_fma_f32 v[134:135], v[134:135], v[204:205], v[200:201]
	s_nop 0
	v_cvt_pk_bf16_f32 v134, v134, v135
	v_cvt_pk_bf16_f32 v135, v132, v133
	global_store_dwordx2 v[100:101], v[134:135], off offset:512
	v_pk_mul_f32 v[132:133], v[54:55], v[140:141] op_sel_hi:[0,1]
	v_pk_mul_f32 v[134:135], v[54:55], v[142:143] op_sel_hi:[0,1]
	v_pk_mul_f32 v[134:135], v[134:135], v[196:197]
	v_pk_mul_f32 v[132:133], v[132:133], v[198:199]
	v_pk_fma_f32 v[134:135], v[134:135], v[204:205], v[200:201]
	v_pk_fma_f32 v[132:133], v[132:133], v[206:207], v[202:203]
	v_cvt_pk_bf16_f32 v134, v134, v135
	v_cvt_pk_bf16_f32 v135, v132, v133
	global_store_dwordx2 v[102:103], v[134:135], off offset:512
	v_pk_mul_f32 v[132:133], v[64:65], v[148:149] op_sel_hi:[0,1]
	v_pk_mul_f32 v[134:135], v[64:65], v[150:151] op_sel_hi:[0,1]
	v_pk_mul_f32 v[134:135], v[134:135], v[196:197]
	v_pk_mul_f32 v[132:133], v[132:133], v[198:199]
	v_pk_fma_f32 v[134:135], v[134:135], v[204:205], v[200:201]
	v_pk_fma_f32 v[132:133], v[132:133], v[206:207], v[202:203]
	v_cvt_pk_bf16_f32 v134, v134, v135
	v_cvt_pk_bf16_f32 v135, v132, v133
	global_store_dwordx2 v[104:105], v[134:135], off offset:512
	v_pk_mul_f32 v[132:133], v[66:67], v[152:153] op_sel_hi:[0,1]
	v_pk_mul_f32 v[134:135], v[66:67], v[154:155] op_sel_hi:[0,1]
	v_pk_mul_f32 v[196:197], v[196:197], v[134:135]
	v_pk_mul_f32 v[198:199], v[198:199], v[132:133]
	v_pk_fma_f32 v[196:197], v[196:197], v[204:205], v[200:201]
	v_pk_fma_f32 v[198:199], v[198:199], v[206:207], v[202:203]
	v_cvt_pk_bf16_f32 v196, v196, v197
	v_cvt_pk_bf16_f32 v197, v198, v199
	global_store_dwordx2 v[106:107], v[196:197], off offset:512
	global_load_dwordx4 v[196:199], v[12:13], off
	global_load_dwordx4 v[200:203], v[250:251], off offset:1024
	global_load_dwordx4 v[204:207], v[252:253], off offset:1024
	s_nop 0
	s_waitcnt vmcnt(17)
	v_pk_mul_f32 v[116:117], v[116:117], v[208:209]
	v_pk_mul_f32 v[118:119], v[118:119], v[210:211]
	v_pk_add_f32 v[220:221], v[220:221], 1.0 op_sel_hi:[1,0]
	v_pk_add_f32 v[218:219], v[218:219], 1.0 op_sel_hi:[1,0]
	v_pk_fma_f32 v[118:119], v[118:119], v[220:221], v[214:215]
	v_pk_fma_f32 v[116:117], v[116:117], v[218:219], v[212:213]
	s_nop 0
	v_cvt_pk_bf16_f32 v116, v116, v117
	v_cvt_pk_bf16_f32 v117, v118, v119
	global_store_dwordx2 v[100:101], v[116:117], off offset:1024
	v_pk_mul_f32 v[116:117], v[54:55], v[126:127] op_sel_hi:[0,1]
	v_pk_mul_f32 v[118:119], v[54:55], v[124:125] op_sel_hi:[0,1]
	v_pk_mul_f32 v[118:119], v[118:119], v[208:209]
	v_pk_mul_f32 v[116:117], v[116:117], v[210:211]
	v_pk_fma_f32 v[118:119], v[118:119], v[218:219], v[212:213]
	v_pk_fma_f32 v[116:117], v[116:117], v[220:221], v[214:215]
	v_cvt_pk_bf16_f32 v118, v118, v119
	v_cvt_pk_bf16_f32 v119, v116, v117
	global_store_dwordx2 v[102:103], v[118:119], off offset:1024
	v_pk_mul_f32 v[116:117], v[64:65], v[138:139] op_sel_hi:[0,1]
	v_pk_mul_f32 v[118:119], v[64:65], v[136:137] op_sel_hi:[0,1]
	v_pk_mul_f32 v[118:119], v[118:119], v[208:209]
	v_pk_mul_f32 v[116:117], v[116:117], v[210:211]
	v_pk_fma_f32 v[118:119], v[118:119], v[218:219], v[212:213]
	v_pk_fma_f32 v[116:117], v[116:117], v[220:221], v[214:215]
	v_cvt_pk_bf16_f32 v118, v118, v119
	v_cvt_pk_bf16_f32 v119, v116, v117
	global_store_dwordx2 v[104:105], v[118:119], off offset:1024
	v_pk_mul_f32 v[116:117], v[66:67], v[146:147] op_sel_hi:[0,1]
	v_pk_mul_f32 v[118:119], v[66:67], v[144:145] op_sel_hi:[0,1]
	v_pk_mul_f32 v[208:209], v[118:119], v[208:209]
	v_pk_mul_f32 v[210:211], v[116:117], v[210:211]
	v_pk_fma_f32 v[208:209], v[208:209], v[218:219], v[212:213]
	v_pk_fma_f32 v[210:211], v[210:211], v[220:221], v[214:215]
	v_cvt_pk_bf16_f32 v208, v208, v209
	v_cvt_pk_bf16_f32 v209, v210, v211
	global_store_dwordx2 v[106:107], v[208:209], off offset:1024
	global_load_dwordx4 v[208:211], v[14:15], off
	global_load_dwordx4 v[212:215], v[250:251], off offset:2048
	global_load_dwordx4 v[218:221], v[252:253], off offset:2048
	s_nop 0
	s_waitcnt vmcnt(21)
	v_pk_mul_f32 v[108:109], v[108:109], v[222:223]
	v_pk_mul_f32 v[110:111], v[110:111], v[224:225]
	v_pk_add_f32 v[244:245], v[244:245], 1.0 op_sel_hi:[1,0]
	v_pk_add_f32 v[242:243], v[242:243], 1.0 op_sel_hi:[1,0]
	v_pk_fma_f32 v[110:111], v[110:111], v[244:245], v[228:229]
	v_pk_fma_f32 v[108:109], v[108:109], v[242:243], v[226:227]
	s_nop 0
	v_cvt_pk_bf16_f32 v108, v108, v109
	v_cvt_pk_bf16_f32 v109, v110, v111
	global_store_dwordx2 v[100:101], v[108:109], off offset:1536
	v_pk_mul_f32 v[108:109], v[54:55], v[114:115] op_sel_hi:[0,1]
	v_pk_mul_f32 v[110:111], v[54:55], v[112:113] op_sel_hi:[0,1]
	v_pk_mul_f32 v[110:111], v[110:111], v[222:223]
	v_pk_mul_f32 v[108:109], v[108:109], v[224:225]
	v_pk_fma_f32 v[110:111], v[110:111], v[242:243], v[226:227]
	v_pk_fma_f32 v[108:109], v[108:109], v[244:245], v[228:229]
	v_cvt_pk_bf16_f32 v110, v110, v111
	v_cvt_pk_bf16_f32 v111, v108, v109
	global_store_dwordx2 v[102:103], v[110:111], off offset:1536
	v_pk_mul_f32 v[108:109], v[64:65], v[122:123] op_sel_hi:[0,1]
	v_pk_mul_f32 v[110:111], v[64:65], v[120:121] op_sel_hi:[0,1]
	v_pk_mul_f32 v[110:111], v[110:111], v[222:223]
	v_pk_mul_f32 v[108:109], v[108:109], v[224:225]
	v_pk_fma_f32 v[110:111], v[110:111], v[242:243], v[226:227]
	v_pk_fma_f32 v[108:109], v[108:109], v[244:245], v[228:229]
	v_cvt_pk_bf16_f32 v110, v110, v111
	v_cvt_pk_bf16_f32 v111, v108, v109
	global_store_dwordx2 v[104:105], v[110:111], off offset:1536
	v_pk_mul_f32 v[108:109], v[66:67], v[130:131] op_sel_hi:[0,1]
	v_pk_mul_f32 v[110:111], v[66:67], v[128:129] op_sel_hi:[0,1]
	v_pk_mul_f32 v[222:223], v[110:111], v[222:223]
	v_pk_mul_f32 v[224:225], v[108:109], v[224:225]
	v_add_co_u32_e32 v108, vcc, s77, v166
	v_pk_fma_f32 v[224:225], v[224:225], v[244:245], v[228:229]
	v_pk_fma_f32 v[222:223], v[222:223], v[242:243], v[226:227]
	v_addc_co_u32_e32 v109, vcc, 0, v167, vcc
	v_cvt_pk_bf16_f32 v222, v222, v223
	v_cvt_pk_bf16_f32 v223, v224, v225
	v_add_co_u32_e32 v110, vcc, s77, v164
	global_store_dwordx2 v[106:107], v[222:223], off offset:1536
	global_load_dwordx4 v[222:225], v[16:17], off
	global_load_dwordx4 v[226:229], v[250:251], off offset:3072
	global_load_dwordx4 v[242:245], v[252:253], off offset:3072
	s_nop 0
	v_addc_co_u32_e32 v111, vcc, 0, v165, vcc
	v_subrev_co_u32_e32 v174, vcc, 1, v174
	s_waitcnt vmcnt(21)
	v_pk_mul_f32 v[84:85], v[84:85], v[180:181]
	v_pk_add_f32 v[112:113], v[186:187], 1.0 op_sel_hi:[1,0]
	v_pk_add_f32 v[184:185], v[184:185], 1.0 op_sel_hi:[1,0]
	v_pk_mul_f32 v[86:87], v[86:87], v[182:183]
	v_pk_fma_f32 v[84:85], v[84:85], v[184:185], v[188:189]
	v_pk_fma_f32 v[86:87], v[86:87], v[112:113], v[190:191]
	v_cvt_pk_bf16_f32 v84, v84, v85
	v_cvt_pk_bf16_f32 v85, v86, v87
	global_store_dwordx2 v[100:101], v[84:85], off offset:2048
	v_pk_mul_f32 v[84:85], v[54:55], v[88:89] op_sel_hi:[0,1]
	v_pk_mul_f32 v[86:87], v[54:55], v[90:91] op_sel_hi:[0,1]
	v_pk_mul_f32 v[86:87], v[86:87], v[180:181]
	v_pk_mul_f32 v[84:85], v[84:85], v[182:183]
	v_pk_fma_f32 v[86:87], v[86:87], v[184:185], v[188:189]
	v_pk_fma_f32 v[84:85], v[84:85], v[112:113], v[190:191]
	v_cvt_pk_bf16_f32 v86, v86, v87
	v_cvt_pk_bf16_f32 v87, v84, v85
	global_store_dwordx2 v[102:103], v[86:87], off offset:2048
	v_pk_mul_f32 v[84:85], v[64:65], v[92:93] op_sel_hi:[0,1]
	v_pk_mul_f32 v[86:87], v[64:65], v[94:95] op_sel_hi:[0,1]
	v_pk_mul_f32 v[86:87], v[86:87], v[180:181]
	v_pk_mul_f32 v[84:85], v[84:85], v[182:183]
	v_pk_fma_f32 v[86:87], v[86:87], v[184:185], v[188:189]
	v_pk_fma_f32 v[84:85], v[84:85], v[112:113], v[190:191]
	v_cvt_pk_bf16_f32 v86, v86, v87
	v_cvt_pk_bf16_f32 v87, v84, v85
	global_store_dwordx2 v[104:105], v[86:87], off offset:2048
	v_pk_mul_f32 v[84:85], v[66:67], v[96:97] op_sel_hi:[0,1]
	v_pk_mul_f32 v[86:87], v[66:67], v[98:99] op_sel_hi:[0,1]
	v_pk_mul_f32 v[180:181], v[86:87], v[180:181]
	v_pk_mul_f32 v[182:183], v[84:85], v[182:183]
	v_pk_fma_f32 v[180:181], v[180:181], v[184:185], v[188:189]
	v_pk_fma_f32 v[182:183], v[182:183], v[112:113], v[190:191]
	v_cvt_pk_bf16_f32 v180, v180, v181
	v_cvt_pk_bf16_f32 v181, v182, v183
	global_store_dwordx2 v[106:107], v[180:181], off offset:2048
	s_nop 0
	s_waitcnt vmcnt(18)
	v_pk_mul_f32 v[80:81], v[80:81], v[196:197]
	v_pk_mul_f32 v[82:83], v[82:83], v[198:199]
	v_pk_add_f32 v[84:85], v[206:207], 1.0 op_sel_hi:[1,0]
	v_pk_add_f32 v[204:205], v[204:205], 1.0 op_sel_hi:[1,0]
	v_pk_mul_f32 v[76:77], v[76:77], v[196:197]
	v_pk_mul_f32 v[78:79], v[78:79], v[198:199]
	v_pk_mul_f32 v[72:73], v[72:73], v[196:197]
	v_pk_mul_f32 v[74:75], v[74:75], v[198:199]
	v_pk_mul_f32 v[196:197], v[68:69], v[196:197]
	v_pk_mul_f32 v[198:199], v[70:71], v[198:199]
	v_pk_fma_f32 v[82:83], v[82:83], v[84:85], v[202:203]
	v_pk_fma_f32 v[80:81], v[80:81], v[204:205], v[200:201]
	v_pk_fma_f32 v[78:79], v[78:79], v[84:85], v[202:203]
	v_pk_fma_f32 v[76:77], v[76:77], v[204:205], v[200:201]
	v_pk_fma_f32 v[74:75], v[74:75], v[84:85], v[202:203]
	v_pk_fma_f32 v[72:73], v[72:73], v[204:205], v[200:201]
	v_pk_fma_f32 v[202:203], v[198:199], v[84:85], v[202:203]
	v_pk_fma_f32 v[200:201], v[196:197], v[204:205], v[200:201]
	v_cvt_pk_bf16_f32 v80, v80, v81
	v_cvt_pk_bf16_f32 v81, v82, v83
	v_cvt_pk_bf16_f32 v76, v76, v77
	v_cvt_pk_bf16_f32 v77, v78, v79
	v_cvt_pk_bf16_f32 v72, v72, v73
	v_cvt_pk_bf16_f32 v73, v74, v75
	v_cvt_pk_bf16_f32 v200, v200, v201
	v_cvt_pk_bf16_f32 v201, v202, v203
	global_store_dwordx2 v[100:101], v[80:81], off offset:2560
	global_store_dwordx2 v[102:103], v[76:77], off offset:2560
	global_store_dwordx2 v[104:105], v[72:73], off offset:2560
	global_store_dwordx2 v[106:107], v[200:201], off offset:2560
	s_nop 0
	s_waitcnt vmcnt(15)
	v_pk_mul_f32 v[56:57], v[56:57], v[208:209]
	v_pk_mul_f32 v[58:59], v[58:59], v[210:211]
	v_pk_add_f32 v[220:221], v[220:221], 1.0 op_sel_hi:[1,0]
	v_pk_add_f32 v[218:219], v[218:219], 1.0 op_sel_hi:[1,0]
	v_pk_fma_f32 v[58:59], v[58:59], v[220:221], v[214:215]
	v_pk_fma_f32 v[56:57], v[56:57], v[218:219], v[212:213]
	v_pk_mul_f32 v[50:51], v[50:51], v[208:209]
	v_cvt_pk_bf16_f32 v56, v56, v57
	v_cvt_pk_bf16_f32 v57, v58, v59
	global_store_dwordx2 v[100:101], v[56:57], off offset:3072
	v_pk_mul_f32 v[56:57], v[54:55], v[62:63] op_sel_hi:[0,1]
	v_pk_mul_f32 v[58:59], v[54:55], v[60:61] op_sel_hi:[0,1]
	v_pk_mul_f32 v[58:59], v[58:59], v[208:209]
	v_pk_mul_f32 v[56:57], v[56:57], v[210:211]
	v_pk_mul_f32 v[52:53], v[52:53], v[210:211]
	v_pk_mul_f32 v[208:209], v[46:47], v[208:209]
	v_pk_mul_f32 v[210:211], v[48:49], v[210:211]
	v_pk_fma_f32 v[56:57], v[56:57], v[220:221], v[214:215]
	v_pk_fma_f32 v[58:59], v[58:59], v[218:219], v[212:213]
	v_pk_fma_f32 v[52:53], v[52:53], v[220:221], v[214:215]
	v_pk_fma_f32 v[50:51], v[50:51], v[218:219], v[212:213]
	v_pk_fma_f32 v[210:211], v[210:211], v[220:221], v[214:215]
	v_pk_fma_f32 v[208:209], v[208:209], v[218:219], v[212:213]
	v_cvt_pk_bf16_f32 v58, v58, v59
	v_cvt_pk_bf16_f32 v59, v56, v57
	v_cvt_pk_bf16_f32 v50, v50, v51
	v_cvt_pk_bf16_f32 v51, v52, v53
	v_cvt_pk_bf16_f32 v208, v208, v209
	v_cvt_pk_bf16_f32 v209, v210, v211
	global_store_dwordx2 v[102:103], v[58:59], off offset:3072
	global_store_dwordx2 v[104:105], v[50:51], off offset:3072
	global_store_dwordx2 v[106:107], v[208:209], off offset:3072
	s_nop 0
	s_waitcnt vmcnt(12)
	v_pk_mul_f32 v[30:31], v[30:31], v[222:223]
	v_pk_mul_f32 v[28:29], v[28:29], v[224:225]
	v_pk_add_f32 v[244:245], v[244:245], 1.0 op_sel_hi:[1,0]
	v_pk_add_f32 v[242:243], v[242:243], 1.0 op_sel_hi:[1,0]
	v_pk_fma_f32 v[28:29], v[28:29], v[244:245], v[228:229]
	v_pk_fma_f32 v[30:31], v[30:31], v[242:243], v[226:227]
	s_nop 0
	v_cvt_pk_bf16_f32 v30, v30, v31
	v_cvt_pk_bf16_f32 v31, v28, v29
	global_store_dwordx2 v[100:101], v[30:31], off offset:3584
	v_pk_mul_f32 v[28:29], v[54:55], v[32:33] op_sel_hi:[0,1]
	v_pk_mul_f32 v[30:31], v[54:55], v[34:35] op_sel_hi:[0,1]
	v_pk_mul_f32 v[30:31], v[30:31], v[222:223]
	v_pk_mul_f32 v[28:29], v[28:29], v[224:225]
	v_pk_fma_f32 v[30:31], v[30:31], v[242:243], v[226:227]
	v_pk_fma_f32 v[28:29], v[28:29], v[244:245], v[228:229]
	v_cvt_pk_bf16_f32 v30, v30, v31
	v_cvt_pk_bf16_f32 v31, v28, v29
	global_store_dwordx2 v[102:103], v[30:31], off offset:3584
	v_pk_mul_f32 v[28:29], v[64:65], v[36:37] op_sel_hi:[0,1]
	v_pk_mul_f32 v[30:31], v[64:65], v[38:39] op_sel_hi:[0,1]
	v_pk_mul_f32 v[30:31], v[30:31], v[222:223]
	v_pk_mul_f32 v[28:29], v[28:29], v[224:225]
	v_pk_fma_f32 v[30:31], v[30:31], v[242:243], v[226:227]
	v_pk_fma_f32 v[28:29], v[28:29], v[244:245], v[228:229]
	v_cvt_pk_bf16_f32 v30, v30, v31
	v_cvt_pk_bf16_f32 v31, v28, v29
	global_store_dwordx2 v[104:105], v[30:31], off offset:3584
	v_pk_mul_f32 v[28:29], v[66:67], v[40:41] op_sel_hi:[0,1]
	v_pk_mul_f32 v[30:31], v[66:67], v[42:43] op_sel_hi:[0,1]
	v_pk_mul_f32 v[222:223], v[30:31], v[222:223]
	v_pk_mul_f32 v[224:225], v[28:29], v[224:225]
	v_pk_fma_f32 v[222:223], v[222:223], v[242:243], v[226:227]
	v_pk_fma_f32 v[224:225], v[224:225], v[244:245], v[228:229]
	v_cvt_pk_bf16_f32 v222, v222, v223
	v_cvt_pk_bf16_f32 v223, v224, v225
	global_store_dwordx2 v[106:107], v[222:223], off offset:3584
	v_cndmask_b32_e64 v0, 0, 1, vcc
	v_cndmask_b32_e64 v1, 0, 1, s[18:19]
	v_cndmask_b32_e64 v0, v1, v0, s[2:3]
	v_and_b32_e32 v0, 1, v0
	v_cmp_eq_u32_e32 vcc, 1, v0
	s_cbranch_vccnz .LBB0_689

.LBB0_1793:
	v_lshl_add_u64 v[0:1], s[16:17], 0, v[18:19]
	v_add_co_u32_e32 v0, vcc, 0x3000000, v0
	v_lshl_add_u64 v[36:37], s[12:13], 0, v[18:19]
	s_nop 0
	v_addc_co_u32_e32 v1, vcc, 0, v1, vcc
	global_load_dwordx2 v[2:3], v[0:1], off
	global_load_dwordx2 v[4:5], v[0:1], off offset:512
	global_load_dwordx2 v[6:7], v[0:1], off offset:1024
	global_load_dwordx2 v[28:29], v[0:1], off offset:1536
	global_load_dwordx2 v[30:31], v[0:1], off offset:2048
	global_load_dwordx2 v[32:33], v[0:1], off offset:2560
	global_load_dwordx2 v[34:35], v[0:1], off offset:3072
	s_nop 0
	global_load_dwordx2 v[0:1], v[0:1], off offset:3584
	v_add_co_u32_e32 v36, vcc, 0x3000000, v36
	s_add_i32 s18, s4, 2
	s_nop 0
	v_addc_co_u32_e32 v37, vcc, 0, v37, vcc
	global_load_dwordx2 v[38:39], v[36:37], off
	global_load_dwordx2 v[40:41], v[36:37], off offset:512
	global_load_dwordx2 v[42:43], v[36:37], off offset:1024
	global_load_dwordx2 v[46:47], v[36:37], off offset:1536
	global_load_dwordx2 v[48:49], v[36:37], off offset:2048
	global_load_dwordx2 v[50:51], v[36:37], off offset:2560
	global_load_dwordx2 v[52:53], v[36:37], off offset:3072
	s_nop 0
	global_load_dwordx2 v[36:37], v[36:37], off offset:3584
	s_ashr_i32 s19, s18, 31
	s_add_i32 s22, s4, 3
	s_lshl_b64 s[18:19], s[18:19], 12
	s_ashr_i32 s23, s22, 31
	v_lshl_add_u64 v[56:57], v[20:21], 0, s[18:19]
	s_lshl_b64 s[22:23], s[22:23], 12
	global_load_dwordx2 v[68:69], v[56:57], off
	global_load_dwordx2 v[70:71], v[56:57], off offset:512
	global_load_dwordx2 v[72:73], v[56:57], off offset:1024
	global_load_dwordx2 v[74:75], v[56:57], off offset:1536
	global_load_dwordx2 v[94:95], v[56:57], off offset:2048
	global_load_dwordx2 v[96:97], v[56:57], off offset:2560
	global_load_dwordx2 v[98:99], v[56:57], off offset:3072
	global_load_dwordx2 v[106:107], v[56:57], off offset:3584
	v_lshl_add_u64 v[56:57], v[20:21], 0, s[22:23]
	global_load_dwordx2 v[128:129], v[56:57], off
	global_load_dwordx2 v[130:131], v[56:57], off offset:512
	global_load_dwordx2 v[146:147], v[56:57], off offset:1024
	global_load_dwordx2 v[164:165], v[56:57], off offset:1536
	global_load_dwordx2 v[166:167], v[56:57], off offset:2048
	global_load_dwordx2 v[168:169], v[56:57], off offset:2560
	global_load_dwordx2 v[170:171], v[56:57], off offset:3072
	global_load_dwordx2 v[176:177], v[56:57], off offset:3584
	s_ashr_i32 s5, s4, 31
	s_lshr_b32 s5, s5, 20
	s_add_i32 s5, s4, s5
	s_ashr_i32 s5, s5, 12
	v_mad_i64_i32 v[230:231], vcc, s5, v237, v[22:23]
	v_mad_i64_i32 v[192:193], vcc, s5, v237, v[24:25]
	v_lshl_add_u64 v[250:251], v[230:231], 0, s[86:87]
	v_lshl_add_u64 v[252:253], v[192:193], 0, s[86:87]
	global_load_dwordx4 v[180:183], v[8:9], off
	global_load_dwordx4 v[184:187], v[230:231], off
	global_load_dwordx4 v[188:191], v[192:193], off
	global_load_dwordx4 v[196:199], v[8:9], off offset:1024
	global_load_dwordx4 v[200:203], v[230:231], off offset:1024
	global_load_dwordx4 v[204:207], v[192:193], off offset:1024
	global_load_dwordx4 v[208:211], v[8:9], off offset:2048
	global_load_dwordx4 v[212:215], v[230:231], off offset:2048
	global_load_dwordx4 v[218:221], v[192:193], off offset:2048
	global_load_dwordx4 v[222:225], v[8:9], off offset:3072
	global_load_dwordx4 v[226:229], v[230:231], off offset:3072
	global_load_dwordx4 v[242:245], v[192:193], off offset:3072
	s_add_i32 s4, s4, s6
	s_cmp_lt_i32 s4, s20
	s_waitcnt vmcnt(43)
	v_cvt_f32_f16_sdwa v163, v2 dst_sel:DWORD dst_unused:UNUSED_PAD src0_sel:WORD_1
	s_waitcnt vmcnt(42)
	v_cvt_f32_f16_sdwa v135, v4 dst_sel:DWORD dst_unused:UNUSED_PAD src0_sel:WORD_1
	v_cvt_f32_f16_sdwa v101, v3 dst_sel:DWORD dst_unused:UNUSED_PAD src0_sel:WORD_1
	v_cvt_f32_f16_e32 v162, v2
	v_cvt_f32_f16_sdwa v133, v5 dst_sel:DWORD dst_unused:UNUSED_PAD src0_sel:WORD_1
	v_cvt_f32_f16_e32 v134, v4
	v_cvt_f32_f16_e32 v100, v3
	v_cvt_f32_f16_e32 v132, v5
	s_waitcnt vmcnt(41)
	v_cvt_f32_f16_e32 v116, v6
	v_cvt_f32_f16_sdwa v117, v6 dst_sel:DWORD dst_unused:UNUSED_PAD src0_sel:WORD_1
	v_cvt_f32_f16_e32 v118, v7
	v_cvt_f32_f16_sdwa v119, v7 dst_sel:DWORD dst_unused:UNUSED_PAD src0_sel:WORD_1
	v_mov_b32_e32 v2, v163
	v_mov_b32_e32 v3, v135
	s_waitcnt vmcnt(40)
	v_cvt_f32_f16_e32 v108, v28
	v_cvt_f32_f16_sdwa v109, v28 dst_sel:DWORD dst_unused:UNUSED_PAD src0_sel:WORD_1
	v_cvt_f32_f16_e32 v110, v29
	v_cvt_f32_f16_sdwa v111, v29 dst_sel:DWORD dst_unused:UNUSED_PAD src0_sel:WORD_1
	s_waitcnt vmcnt(39)
	v_cvt_f32_f16_sdwa v87, v31 dst_sel:DWORD dst_unused:UNUSED_PAD src0_sel:WORD_1
	v_cvt_f32_f16_e32 v86, v31
	v_cvt_f32_f16_sdwa v85, v30 dst_sel:DWORD dst_unused:UNUSED_PAD src0_sel:WORD_1
	v_cvt_f32_f16_e32 v84, v30
	s_waitcnt vmcnt(36)
	v_cvt_f32_f16_sdwa v29, v1 dst_sel:DWORD dst_unused:UNUSED_PAD src0_sel:WORD_1
	v_cvt_f32_f16_e32 v28, v1
	v_cvt_f32_f16_sdwa v31, v0 dst_sel:DWORD dst_unused:UNUSED_PAD src0_sel:WORD_1
	v_cvt_f32_f16_e32 v30, v0
	v_mov_b32_e32 v0, v162
	v_mov_b32_e32 v1, v134
	v_pk_mul_f32 v[2:3], v[2:3], v[2:3]
	v_mov_b32_e32 v4, v101
	v_mov_b32_e32 v5, v133
	v_pk_fma_f32 v[0:1], v[0:1], v[0:1], v[2:3]
	v_mov_b32_e32 v2, v100
	v_mov_b32_e32 v3, v132
	v_pk_mul_f32 v[4:5], v[4:5], v[4:5]
	v_cvt_f32_f16_e32 v80, v32
	v_pk_fma_f32 v[2:3], v[2:3], v[2:3], v[4:5]
	v_pk_mul_f32 v[4:5], v[116:117], v[116:117]
	v_pk_add_f32 v[0:1], v[0:1], v[2:3]
	v_pk_mul_f32 v[2:3], v[118:119], v[118:119]
	v_pk_add_f32 v[0:1], v[0:1], v[0:1] op_sel:[0,1] op_sel_hi:[1,0]
	v_pk_mov_b32 v[6:7], v[4:5], v[2:3] op_sel:[1,0]
	v_mov_b32_e32 v5, v3
	v_pk_add_f32 v[2:3], v[6:7], v[4:5]
	v_mul_f32_e32 v4, v84, v84
	v_mul_f32_e32 v5, v85, v85
	v_pk_add_f32 v[2:3], v[2:3], v[2:3] op_sel:[0,1] op_sel_hi:[1,0]
	v_mov_b32_e32 v1, v4
	v_mov_b32_e32 v3, v5
	v_cvt_f32_f16_sdwa v81, v32 dst_sel:DWORD dst_unused:UNUSED_PAD src0_sel:WORD_1
	v_cvt_f32_f16_e32 v82, v33
	v_cvt_f32_f16_sdwa v83, v33 dst_sel:DWORD dst_unused:UNUSED_PAD src0_sel:WORD_1
	v_pk_add_f32 v[0:1], v[0:1], v[2:3]
	v_mul_f32_e32 v2, v109, v109
	v_mul_f32_e32 v4, v111, v111
	v_mul_f32_e32 v6, v86, v86
	v_mul_f32_e32 v7, v87, v87
	v_pk_fma_f32 v[2:3], v[108:109], v[108:109], v[2:3] op_sel_hi:[1,1,0]
	v_pk_fma_f32 v[4:5], v[110:111], v[110:111], v[4:5] op_sel_hi:[1,1,0]
	v_mov_b32_e32 v3, v6
	v_mov_b32_e32 v5, v7
	v_pk_add_f32 v[2:3], v[2:3], v[4:5]
	v_pk_mul_f32 v[4:5], v[80:81], v[80:81]
	v_pk_add_f32 v[0:1], v[0:1], v[2:3]
	v_pk_mul_f32 v[2:3], v[82:83], v[82:83]
	v_cvt_f32_f16_sdwa v57, v34 dst_sel:DWORD dst_unused:UNUSED_PAD src0_sel:WORD_1
	v_cvt_f32_f16_sdwa v59, v35 dst_sel:DWORD dst_unused:UNUSED_PAD src0_sel:WORD_1
	v_pk_mov_b32 v[6:7], v[4:5], v[2:3] op_sel:[1,0]
	v_mov_b32_e32 v5, v3
	v_cvt_f32_f16_e32 v56, v34
	v_cvt_f32_f16_e32 v58, v35
	v_pk_add_f32 v[2:3], v[6:7], v[4:5]
	v_mul_f32_e32 v4, v30, v30
	v_mul_f32_e32 v5, v31, v31
	v_pk_add_f32 v[0:1], v[0:1], v[0:1] op_sel:[0,1] op_sel_hi:[1,0]
	v_pk_add_f32 v[2:3], v[2:3], v[2:3] op_sel:[0,1] op_sel_hi:[1,0]
	v_mov_b32_e32 v1, v4
	v_mov_b32_e32 v3, v5
	v_pk_add_f32 v[0:1], v[0:1], v[2:3]
	v_mul_f32_e32 v2, v57, v57
	v_mul_f32_e32 v4, v59, v59
	v_mul_f32_e32 v6, v28, v28
	v_mul_f32_e32 v7, v29, v29
	v_pk_fma_f32 v[2:3], v[56:57], v[56:57], v[2:3] op_sel_hi:[1,1,0]
	v_pk_fma_f32 v[4:5], v[58:59], v[58:59], v[4:5] op_sel_hi:[1,1,0]
	v_mov_b32_e32 v3, v6
	v_mov_b32_e32 v5, v7
	v_pk_add_f32 v[2:3], v[2:3], v[4:5]
	s_waitcnt vmcnt(35)
	v_cvt_f32_f16_sdwa v161, v38 dst_sel:DWORD dst_unused:UNUSED_PAD src0_sel:WORD_1
	v_pk_add_f32 v[0:1], v[0:1], v[2:3]
	s_waitcnt vmcnt(34)
	v_cvt_f32_f16_sdwa v143, v40 dst_sel:DWORD dst_unused:UNUSED_PAD src0_sel:WORD_1
	v_add_f32_e32 v0, v0, v1
	v_cvt_f32_f16_sdwa v103, v39 dst_sel:DWORD dst_unused:UNUSED_PAD src0_sel:WORD_1
	v_cvt_f32_f16_e32 v160, v38
	v_cvt_f32_f16_sdwa v141, v41 dst_sel:DWORD dst_unused:UNUSED_PAD src0_sel:WORD_1
	v_cvt_f32_f16_e32 v142, v40
	s_waitcnt lgkmcnt(0)
	s_nop 1
	v_add_f32_dpp v0, v0, v0 quad_perm:[1,0,3,2] row_mask:0xf bank_mask:0xf
	v_cvt_f32_f16_e32 v102, v39
	v_cvt_f32_f16_e32 v140, v41
	s_waitcnt vmcnt(33)
	v_cvt_f32_f16_e32 v124, v42
	v_cvt_f32_f16_sdwa v125, v42 dst_sel:DWORD dst_unused:UNUSED_PAD src0_sel:WORD_1
	s_waitcnt lgkmcnt(0)
	s_nop 1
	v_add_f32_dpp v0, v0, v0 quad_perm:[2,3,0,1] row_mask:0xf bank_mask:0xf
	v_cvt_f32_f16_e32 v126, v43
	v_cvt_f32_f16_sdwa v127, v43 dst_sel:DWORD dst_unused:UNUSED_PAD src0_sel:WORD_1
	v_mov_b32_e32 v2, v161
	v_mov_b32_e32 v3, v143
	s_waitcnt lgkmcnt(0)
	s_nop 1
	v_add_f32_dpp v0, v0, v0 row_half_mirror row_mask:0xf bank_mask:0xf
	v_pk_mul_f32 v[2:3], v[2:3], v[2:3]
	v_mov_b32_e32 v4, v103
	v_mov_b32_e32 v5, v141
	v_pk_mul_f32 v[4:5], v[4:5], v[4:5]
	s_waitcnt lgkmcnt(0)
	s_nop 1
	v_add_f32_dpp v0, v0, v0 row_mirror row_mask:0xf bank_mask:0xf
	s_waitcnt vmcnt(31)
	v_cvt_f32_f16_sdwa v91, v48 dst_sel:DWORD dst_unused:UNUSED_PAD src0_sel:WORD_1
	v_cvt_f32_f16_e32 v90, v48
	v_cvt_f32_f16_sdwa v113, v46 dst_sel:DWORD dst_unused:UNUSED_PAD src0_sel:WORD_1
	v_cvt_f32_f16_sdwa v115, v47 dst_sel:DWORD dst_unused:UNUSED_PAD src0_sel:WORD_1
	s_waitcnt lgkmcnt(0)
	v_mov_b32_e32 v1, v0
	s_nop 1
	v_permlane16_swap_b32_e32 v0, v1
	s_nop 0
	v_add_f32_e32 v0, v0, v1
	v_cvt_f32_f16_e32 v112, v46
	v_cvt_f32_f16_e32 v114, v47
	v_cvt_f32_f16_sdwa v89, v49 dst_sel:DWORD dst_unused:UNUSED_PAD src0_sel:WORD_1
	v_cvt_f32_f16_e32 v88, v49
	s_waitcnt lgkmcnt(0)
	v_mov_b32_e32 v1, v0
	s_nop 1
	v_permlane32_swap_b32_e32 v0, v1
	s_nop 0
	v_add_f32_e32 v0, v0, v1
	v_fmamk_f32 v0, v0, 0x3a000000, v232
	v_rsq_f32_e32 v44, v0
	v_mov_b32_e32 v0, v160
	v_mov_b32_e32 v1, v142
	v_pk_fma_f32 v[0:1], v[0:1], v[0:1], v[2:3]
	v_mov_b32_e32 v2, v102
	v_mov_b32_e32 v3, v140
	v_pk_fma_f32 v[2:3], v[2:3], v[2:3], v[4:5]
	v_pk_mul_f32 v[4:5], v[124:125], v[124:125]
	v_pk_add_f32 v[0:1], v[0:1], v[2:3]
	v_pk_mul_f32 v[2:3], v[126:127], v[126:127]
	v_pk_add_f32 v[0:1], v[0:1], v[0:1] op_sel:[0,1] op_sel_hi:[1,0]
	v_pk_mov_b32 v[6:7], v[4:5], v[2:3] op_sel:[1,0]
	v_mov_b32_e32 v5, v3
	v_pk_add_f32 v[2:3], v[6:7], v[4:5]
	v_mul_f32_e32 v4, v90, v90
	v_mul_f32_e32 v5, v91, v91
	v_pk_add_f32 v[2:3], v[2:3], v[2:3] op_sel:[0,1] op_sel_hi:[1,0]
	v_mov_b32_e32 v1, v4
	v_mov_b32_e32 v3, v5
	s_waitcnt vmcnt(30)
	v_cvt_f32_f16_e32 v76, v50
	v_cvt_f32_f16_sdwa v77, v50 dst_sel:DWORD dst_unused:UNUSED_PAD src0_sel:WORD_1
	v_cvt_f32_f16_e32 v78, v51
	v_cvt_f32_f16_sdwa v79, v51 dst_sel:DWORD dst_unused:UNUSED_PAD src0_sel:WORD_1
	v_pk_add_f32 v[0:1], v[0:1], v[2:3]
	v_mul_f32_e32 v2, v113, v113
	v_mul_f32_e32 v4, v115, v115
	v_mul_f32_e32 v6, v88, v88
	v_mul_f32_e32 v7, v89, v89
	v_pk_fma_f32 v[2:3], v[112:113], v[112:113], v[2:3] op_sel_hi:[1,1,0]
	v_pk_fma_f32 v[4:5], v[114:115], v[114:115], v[4:5] op_sel_hi:[1,1,0]
	v_mov_b32_e32 v3, v6
	v_mov_b32_e32 v5, v7
	s_waitcnt vmcnt(28)
	v_cvt_f32_f16_sdwa v35, v36 dst_sel:DWORD dst_unused:UNUSED_PAD src0_sel:WORD_1
	v_cvt_f32_f16_e32 v34, v36
	v_pk_add_f32 v[2:3], v[2:3], v[4:5]
	v_pk_mul_f32 v[4:5], v[76:77], v[76:77]
	v_pk_add_f32 v[0:1], v[0:1], v[2:3]
	v_pk_mul_f32 v[2:3], v[78:79], v[78:79]
	v_cvt_f32_f16_sdwa v61, v52 dst_sel:DWORD dst_unused:UNUSED_PAD src0_sel:WORD_1
	v_cvt_f32_f16_sdwa v63, v53 dst_sel:DWORD dst_unused:UNUSED_PAD src0_sel:WORD_1
	v_pk_mov_b32 v[6:7], v[4:5], v[2:3] op_sel:[1,0]
	v_mov_b32_e32 v5, v3
	v_cvt_f32_f16_e32 v60, v52
	v_cvt_f32_f16_e32 v62, v53
	v_cvt_f32_f16_sdwa v33, v37 dst_sel:DWORD dst_unused:UNUSED_PAD src0_sel:WORD_1
	v_cvt_f32_f16_e32 v32, v37
	v_pk_add_f32 v[2:3], v[6:7], v[4:5]
	v_mul_f32_e32 v4, v34, v34
	v_mul_f32_e32 v5, v35, v35
	v_pk_add_f32 v[0:1], v[0:1], v[0:1] op_sel:[0,1] op_sel_hi:[1,0]
	v_pk_add_f32 v[2:3], v[2:3], v[2:3] op_sel:[0,1] op_sel_hi:[1,0]
	v_mov_b32_e32 v1, v4
	v_mov_b32_e32 v3, v5
	v_pk_add_f32 v[0:1], v[0:1], v[2:3]
	v_mul_f32_e32 v2, v61, v61
	v_mul_f32_e32 v4, v63, v63
	v_mul_f32_e32 v6, v32, v32
	v_mul_f32_e32 v7, v33, v33
	v_pk_fma_f32 v[2:3], v[60:61], v[60:61], v[2:3] op_sel_hi:[1,1,0]
	v_pk_fma_f32 v[4:5], v[62:63], v[62:63], v[4:5] op_sel_hi:[1,1,0]
	v_mov_b32_e32 v3, v6
	v_mov_b32_e32 v5, v7
	v_pk_add_f32 v[2:3], v[2:3], v[4:5]
	s_waitcnt vmcnt(27)
	v_cvt_f32_f16_sdwa v159, v68 dst_sel:DWORD dst_unused:UNUSED_PAD src0_sel:WORD_1
	v_pk_add_f32 v[0:1], v[0:1], v[2:3]
	s_waitcnt vmcnt(26)
	v_cvt_f32_f16_sdwa v151, v70 dst_sel:DWORD dst_unused:UNUSED_PAD src0_sel:WORD_1
	v_add_f32_e32 v0, v0, v1
	v_cvt_f32_f16_sdwa v105, v69 dst_sel:DWORD dst_unused:UNUSED_PAD src0_sel:WORD_1
	v_cvt_f32_f16_e32 v158, v68
	v_cvt_f32_f16_sdwa v149, v71 dst_sel:DWORD dst_unused:UNUSED_PAD src0_sel:WORD_1
	v_cvt_f32_f16_e32 v150, v70
	s_waitcnt lgkmcnt(0)
	s_nop 1
	v_add_f32_dpp v0, v0, v0 quad_perm:[1,0,3,2] row_mask:0xf bank_mask:0xf
	v_cvt_f32_f16_e32 v104, v69
	v_cvt_f32_f16_e32 v148, v71
	s_waitcnt vmcnt(25)
	v_cvt_f32_f16_e32 v136, v72
	v_cvt_f32_f16_sdwa v137, v72 dst_sel:DWORD dst_unused:UNUSED_PAD src0_sel:WORD_1
	s_waitcnt lgkmcnt(0)
	s_nop 1
	v_add_f32_dpp v0, v0, v0 quad_perm:[2,3,0,1] row_mask:0xf bank_mask:0xf
	v_cvt_f32_f16_e32 v138, v73
	v_cvt_f32_f16_sdwa v139, v73 dst_sel:DWORD dst_unused:UNUSED_PAD src0_sel:WORD_1
	v_mov_b32_e32 v2, v159
	v_mov_b32_e32 v3, v151
	s_waitcnt lgkmcnt(0)
	s_nop 1
	v_add_f32_dpp v0, v0, v0 row_half_mirror row_mask:0xf bank_mask:0xf
	v_pk_mul_f32 v[2:3], v[2:3], v[2:3]
	v_mov_b32_e32 v4, v105
	v_mov_b32_e32 v5, v149
	v_pk_mul_f32 v[4:5], v[4:5], v[4:5]
	s_waitcnt lgkmcnt(0)
	s_nop 1
	v_add_f32_dpp v0, v0, v0 row_mirror row_mask:0xf bank_mask:0xf
	s_waitcnt vmcnt(23)
	v_cvt_f32_f16_sdwa v93, v95 dst_sel:DWORD dst_unused:UNUSED_PAD src0_sel:WORD_1
	v_cvt_f32_f16_e32 v92, v95
	v_cvt_f32_f16_sdwa v95, v94 dst_sel:DWORD dst_unused:UNUSED_PAD src0_sel:WORD_1
	v_cvt_f32_f16_e32 v94, v94
	s_waitcnt lgkmcnt(0)
	v_mov_b32_e32 v1, v0
	s_nop 1
	v_permlane16_swap_b32_e32 v0, v1
	s_nop 0
	v_add_f32_e32 v0, v0, v1
	v_cvt_f32_f16_sdwa v121, v74 dst_sel:DWORD dst_unused:UNUSED_PAD src0_sel:WORD_1
	v_cvt_f32_f16_sdwa v123, v75 dst_sel:DWORD dst_unused:UNUSED_PAD src0_sel:WORD_1
	v_cvt_f32_f16_e32 v120, v74
	v_cvt_f32_f16_e32 v122, v75
	s_waitcnt lgkmcnt(0)
	v_mov_b32_e32 v1, v0
	s_nop 1
	v_permlane32_swap_b32_e32 v0, v1
	s_nop 0
	v_add_f32_e32 v0, v0, v1
	v_fmamk_f32 v0, v0, 0x3a000000, v232
	v_rsq_f32_e32 v54, v0
	v_mov_b32_e32 v0, v158
	v_mov_b32_e32 v1, v150
	v_pk_fma_f32 v[0:1], v[0:1], v[0:1], v[2:3]
	v_mov_b32_e32 v2, v104
	v_mov_b32_e32 v3, v148
	v_pk_fma_f32 v[2:3], v[2:3], v[2:3], v[4:5]
	v_pk_mul_f32 v[4:5], v[136:137], v[136:137]
	v_pk_add_f32 v[0:1], v[0:1], v[2:3]
	v_pk_mul_f32 v[2:3], v[138:139], v[138:139]
	v_pk_add_f32 v[0:1], v[0:1], v[0:1] op_sel:[0,1] op_sel_hi:[1,0]
	v_pk_mov_b32 v[6:7], v[4:5], v[2:3] op_sel:[1,0]
	v_mov_b32_e32 v5, v3
	v_pk_add_f32 v[2:3], v[6:7], v[4:5]
	v_mul_f32_e32 v4, v94, v94
	v_mul_f32_e32 v5, v95, v95
	v_pk_add_f32 v[2:3], v[2:3], v[2:3] op_sel:[0,1] op_sel_hi:[1,0]
	v_mov_b32_e32 v1, v4
	v_mov_b32_e32 v3, v5
	s_waitcnt vmcnt(22)
	v_cvt_f32_f16_e32 v72, v96
	v_cvt_f32_f16_sdwa v73, v96 dst_sel:DWORD dst_unused:UNUSED_PAD src0_sel:WORD_1
	v_cvt_f32_f16_e32 v74, v97
	v_cvt_f32_f16_sdwa v75, v97 dst_sel:DWORD dst_unused:UNUSED_PAD src0_sel:WORD_1
	v_pk_add_f32 v[0:1], v[0:1], v[2:3]
	v_mul_f32_e32 v2, v121, v121
	v_mul_f32_e32 v4, v123, v123
	v_mul_f32_e32 v6, v92, v92
	v_mul_f32_e32 v7, v93, v93
	v_pk_fma_f32 v[2:3], v[120:121], v[120:121], v[2:3] op_sel_hi:[1,1,0]
	v_pk_fma_f32 v[4:5], v[122:123], v[122:123], v[4:5] op_sel_hi:[1,1,0]
	v_mov_b32_e32 v3, v6
	v_mov_b32_e32 v5, v7
	s_waitcnt vmcnt(20)
	v_cvt_f32_f16_sdwa v39, v106 dst_sel:DWORD dst_unused:UNUSED_PAD src0_sel:WORD_1
	v_cvt_f32_f16_e32 v38, v106
	v_pk_add_f32 v[2:3], v[2:3], v[4:5]
	v_pk_mul_f32 v[4:5], v[72:73], v[72:73]
	v_pk_add_f32 v[0:1], v[0:1], v[2:3]
	v_pk_mul_f32 v[2:3], v[74:75], v[74:75]
	v_cvt_f32_f16_sdwa v51, v98 dst_sel:DWORD dst_unused:UNUSED_PAD src0_sel:WORD_1
	v_cvt_f32_f16_sdwa v53, v99 dst_sel:DWORD dst_unused:UNUSED_PAD src0_sel:WORD_1
	v_pk_mov_b32 v[6:7], v[4:5], v[2:3] op_sel:[1,0]
	v_mov_b32_e32 v5, v3
	v_cvt_f32_f16_e32 v50, v98
	v_cvt_f32_f16_e32 v52, v99
	v_cvt_f32_f16_sdwa v37, v107 dst_sel:DWORD dst_unused:UNUSED_PAD src0_sel:WORD_1
	v_cvt_f32_f16_e32 v36, v107
	v_pk_add_f32 v[2:3], v[6:7], v[4:5]
	v_mul_f32_e32 v4, v38, v38
	v_mul_f32_e32 v5, v39, v39
	v_pk_add_f32 v[0:1], v[0:1], v[0:1] op_sel:[0,1] op_sel_hi:[1,0]
	v_pk_add_f32 v[2:3], v[2:3], v[2:3] op_sel:[0,1] op_sel_hi:[1,0]
	v_mov_b32_e32 v1, v4
	v_mov_b32_e32 v3, v5
	v_pk_add_f32 v[0:1], v[0:1], v[2:3]
	v_mul_f32_e32 v2, v51, v51
	v_mul_f32_e32 v4, v53, v53
	v_mul_f32_e32 v6, v36, v36
	v_mul_f32_e32 v7, v37, v37
	v_pk_fma_f32 v[2:3], v[50:51], v[50:51], v[2:3] op_sel_hi:[1,1,0]
	v_pk_fma_f32 v[4:5], v[52:53], v[52:53], v[4:5] op_sel_hi:[1,1,0]
	v_mov_b32_e32 v3, v6
	v_mov_b32_e32 v5, v7
	v_pk_add_f32 v[2:3], v[2:3], v[4:5]
	s_waitcnt vmcnt(19)
	v_cvt_f32_f16_sdwa v157, v128 dst_sel:DWORD dst_unused:UNUSED_PAD src0_sel:WORD_1
	v_pk_add_f32 v[0:1], v[0:1], v[2:3]
	s_waitcnt vmcnt(18)
	v_cvt_f32_f16_sdwa v155, v130 dst_sel:DWORD dst_unused:UNUSED_PAD src0_sel:WORD_1
	v_add_f32_e32 v0, v0, v1
	v_cvt_f32_f16_sdwa v107, v129 dst_sel:DWORD dst_unused:UNUSED_PAD src0_sel:WORD_1
	v_cvt_f32_f16_e32 v156, v128
	v_cvt_f32_f16_sdwa v153, v131 dst_sel:DWORD dst_unused:UNUSED_PAD src0_sel:WORD_1
	v_cvt_f32_f16_e32 v154, v130
	s_waitcnt lgkmcnt(0)
	s_nop 1
	v_add_f32_dpp v0, v0, v0 quad_perm:[1,0,3,2] row_mask:0xf bank_mask:0xf
	v_cvt_f32_f16_e32 v106, v129
	v_cvt_f32_f16_e32 v152, v131
	s_waitcnt vmcnt(17)
	v_cvt_f32_f16_e32 v144, v146
	v_cvt_f32_f16_sdwa v145, v146 dst_sel:DWORD dst_unused:UNUSED_PAD src0_sel:WORD_1
	s_waitcnt lgkmcnt(0)
	s_nop 1
	v_add_f32_dpp v0, v0, v0 quad_perm:[2,3,0,1] row_mask:0xf bank_mask:0xf
	v_cvt_f32_f16_e32 v146, v147
	v_cvt_f32_f16_sdwa v147, v147 dst_sel:DWORD dst_unused:UNUSED_PAD src0_sel:WORD_1
	v_mov_b32_e32 v2, v157
	v_mov_b32_e32 v3, v155
	s_waitcnt lgkmcnt(0)
	s_nop 1
	v_add_f32_dpp v0, v0, v0 row_half_mirror row_mask:0xf bank_mask:0xf
	v_pk_mul_f32 v[2:3], v[2:3], v[2:3]
	v_mov_b32_e32 v4, v107
	v_mov_b32_e32 v5, v153
	v_pk_mul_f32 v[4:5], v[4:5], v[4:5]
	s_waitcnt lgkmcnt(0)
	s_nop 1
	v_add_f32_dpp v0, v0, v0 row_mirror row_mask:0xf bank_mask:0xf
	s_waitcnt vmcnt(15)
	v_cvt_f32_f16_sdwa v99, v166 dst_sel:DWORD dst_unused:UNUSED_PAD src0_sel:WORD_1
	v_cvt_f32_f16_e32 v98, v166
	v_cvt_f32_f16_sdwa v129, v164 dst_sel:DWORD dst_unused:UNUSED_PAD src0_sel:WORD_1
	v_cvt_f32_f16_sdwa v131, v165 dst_sel:DWORD dst_unused:UNUSED_PAD src0_sel:WORD_1
	s_waitcnt lgkmcnt(0)
	v_mov_b32_e32 v1, v0
	s_nop 1
	v_permlane16_swap_b32_e32 v0, v1
	s_nop 0
	v_add_f32_e32 v0, v0, v1
	v_cvt_f32_f16_e32 v128, v164
	v_cvt_f32_f16_e32 v130, v165
	v_cvt_f32_f16_sdwa v97, v167 dst_sel:DWORD dst_unused:UNUSED_PAD src0_sel:WORD_1
	v_cvt_f32_f16_e32 v96, v167
	s_waitcnt lgkmcnt(0)
	v_mov_b32_e32 v1, v0
	s_nop 1
	v_permlane32_swap_b32_e32 v0, v1
	s_nop 0
	v_add_f32_e32 v0, v0, v1
	v_fmamk_f32 v0, v0, 0x3a000000, v232
	v_rsq_f32_e32 v64, v0
	v_mov_b32_e32 v0, v156
	v_mov_b32_e32 v1, v154
	v_pk_fma_f32 v[0:1], v[0:1], v[0:1], v[2:3]
	v_mov_b32_e32 v2, v106
	v_mov_b32_e32 v3, v152
	v_pk_fma_f32 v[2:3], v[2:3], v[2:3], v[4:5]
	v_pk_mul_f32 v[4:5], v[144:145], v[144:145]
	v_pk_add_f32 v[0:1], v[0:1], v[2:3]
	v_pk_mul_f32 v[2:3], v[146:147], v[146:147]
	v_pk_add_f32 v[0:1], v[0:1], v[0:1] op_sel:[0,1] op_sel_hi:[1,0]
	v_pk_mov_b32 v[6:7], v[4:5], v[2:3] op_sel:[1,0]
	v_mov_b32_e32 v5, v3
	v_pk_add_f32 v[2:3], v[6:7], v[4:5]
	v_mul_f32_e32 v4, v98, v98
	v_mul_f32_e32 v5, v99, v99
	v_pk_add_f32 v[2:3], v[2:3], v[2:3] op_sel:[0,1] op_sel_hi:[1,0]
	v_mov_b32_e32 v1, v4
	v_mov_b32_e32 v3, v5
	s_waitcnt vmcnt(14)
	v_cvt_f32_f16_e32 v68, v168
	v_cvt_f32_f16_sdwa v69, v168 dst_sel:DWORD dst_unused:UNUSED_PAD src0_sel:WORD_1
	v_cvt_f32_f16_e32 v70, v169
	v_cvt_f32_f16_sdwa v71, v169 dst_sel:DWORD dst_unused:UNUSED_PAD src0_sel:WORD_1
	v_pk_add_f32 v[0:1], v[0:1], v[2:3]
	v_mul_f32_e32 v2, v129, v129
	v_mul_f32_e32 v4, v131, v131
	v_mul_f32_e32 v6, v96, v96
	v_mul_f32_e32 v7, v97, v97
	v_pk_fma_f32 v[2:3], v[128:129], v[128:129], v[2:3] op_sel_hi:[1,1,0]
	v_pk_fma_f32 v[4:5], v[130:131], v[130:131], v[4:5] op_sel_hi:[1,1,0]
	v_mov_b32_e32 v3, v6
	v_mov_b32_e32 v5, v7
	s_waitcnt vmcnt(12)
	v_cvt_f32_f16_sdwa v43, v176 dst_sel:DWORD dst_unused:UNUSED_PAD src0_sel:WORD_1
	v_cvt_f32_f16_e32 v42, v176
	v_pk_add_f32 v[2:3], v[2:3], v[4:5]
	v_pk_mul_f32 v[4:5], v[68:69], v[68:69]
	v_pk_add_f32 v[0:1], v[0:1], v[2:3]
	v_pk_mul_f32 v[2:3], v[70:71], v[70:71]
	v_cvt_f32_f16_sdwa v47, v170 dst_sel:DWORD dst_unused:UNUSED_PAD src0_sel:WORD_1
	v_cvt_f32_f16_sdwa v49, v171 dst_sel:DWORD dst_unused:UNUSED_PAD src0_sel:WORD_1
	v_pk_mov_b32 v[6:7], v[4:5], v[2:3] op_sel:[1,0]
	v_mov_b32_e32 v5, v3
	v_cvt_f32_f16_e32 v46, v170
	v_cvt_f32_f16_e32 v48, v171
	v_cvt_f32_f16_sdwa v41, v177 dst_sel:DWORD dst_unused:UNUSED_PAD src0_sel:WORD_1
	v_cvt_f32_f16_e32 v40, v177
	v_pk_add_f32 v[2:3], v[6:7], v[4:5]
	v_mul_f32_e32 v4, v42, v42
	v_mul_f32_e32 v5, v43, v43
	v_pk_add_f32 v[0:1], v[0:1], v[0:1] op_sel:[0,1] op_sel_hi:[1,0]
	v_pk_add_f32 v[2:3], v[2:3], v[2:3] op_sel:[0,1] op_sel_hi:[1,0]
	v_mov_b32_e32 v1, v4
	v_mov_b32_e32 v3, v5
	v_pk_add_f32 v[0:1], v[0:1], v[2:3]
	v_mul_f32_e32 v2, v47, v47
	v_mul_f32_e32 v4, v49, v49
	v_mul_f32_e32 v6, v40, v40
	v_mul_f32_e32 v7, v41, v41
	v_pk_fma_f32 v[2:3], v[46:47], v[46:47], v[2:3] op_sel_hi:[1,1,0]
	v_pk_fma_f32 v[4:5], v[48:49], v[48:49], v[4:5] op_sel_hi:[1,1,0]
	v_mov_b32_e32 v3, v6
	v_mov_b32_e32 v5, v7
	v_pk_add_f32 v[2:3], v[2:3], v[4:5]
	v_mad_i64_i32 v[166:167], s[52:53], s5, v237, v[22:23]
	v_pk_add_f32 v[0:1], v[0:1], v[2:3]
	v_mad_i64_i32 v[164:165], s[52:53], s5, v237, v[24:25]
	v_add_f32_e32 v0, v0, v1
	v_pk_mul_f32 v[100:101], v[44:45], v[100:101] op_sel_hi:[0,1]
	v_pk_mul_f32 v[162:163], v[44:45], v[162:163] op_sel_hi:[0,1]
	v_pk_mul_f32 v[102:103], v[54:55], v[102:103] op_sel_hi:[0,1]
	v_pk_mul_f32 v[160:161], v[54:55], v[160:161] op_sel_hi:[0,1]
	s_waitcnt lgkmcnt(0)
	s_nop 1
	v_add_f32_dpp v0, v0, v0 quad_perm:[1,0,3,2] row_mask:0xf bank_mask:0xf
	v_pk_mul_f32 v[104:105], v[64:65], v[104:105] op_sel_hi:[0,1]
	v_pk_mul_f32 v[158:159], v[64:65], v[158:159] op_sel_hi:[0,1]
	v_pk_mul_f32 v[132:133], v[44:45], v[132:133] op_sel_hi:[0,1]
	v_pk_mul_f32 v[134:135], v[44:45], v[134:135] op_sel_hi:[0,1]
	s_waitcnt lgkmcnt(0)
	s_nop 1
	v_add_f32_dpp v0, v0, v0 quad_perm:[2,3,0,1] row_mask:0xf bank_mask:0xf
	v_pk_mul_f32 v[118:119], v[44:45], v[118:119] op_sel_hi:[0,1]
	v_pk_mul_f32 v[116:117], v[44:45], v[116:117] op_sel_hi:[0,1]
	v_pk_mul_f32 v[110:111], v[44:45], v[110:111] op_sel_hi:[0,1]
	v_pk_mul_f32 v[108:109], v[44:45], v[108:109] op_sel_hi:[0,1]
	s_waitcnt lgkmcnt(0)
	s_nop 1
	v_add_f32_dpp v0, v0, v0 row_half_mirror row_mask:0xf bank_mask:0xf
	v_pk_mul_f32 v[86:87], v[44:45], v[86:87] op_sel_hi:[0,1]
	v_pk_mul_f32 v[84:85], v[44:45], v[84:85] op_sel_hi:[0,1]
	v_pk_mul_f32 v[82:83], v[44:45], v[82:83] op_sel_hi:[0,1]
	v_pk_mul_f32 v[80:81], v[44:45], v[80:81] op_sel_hi:[0,1]
	s_waitcnt lgkmcnt(0)
	s_nop 1
	v_add_f32_dpp v0, v0, v0 row_mirror row_mask:0xf bank_mask:0xf
	v_pk_mul_f32 v[78:79], v[54:55], v[78:79] op_sel_hi:[0,1]
	v_pk_mul_f32 v[76:77], v[54:55], v[76:77] op_sel_hi:[0,1]
	v_pk_mul_f32 v[74:75], v[64:65], v[74:75] op_sel_hi:[0,1]
	v_pk_mul_f32 v[72:73], v[64:65], v[72:73] op_sel_hi:[0,1]
	s_waitcnt lgkmcnt(0)
	v_mov_b32_e32 v1, v0
	s_nop 1
	v_permlane16_swap_b32_e32 v0, v1
	s_nop 0
	v_add_f32_e32 v0, v0, v1
	v_pk_mul_f32 v[58:59], v[44:45], v[58:59] op_sel_hi:[0,1]
	v_pk_mul_f32 v[56:57], v[44:45], v[56:57] op_sel_hi:[0,1]
	v_pk_mul_f32 v[52:53], v[64:65], v[52:53] op_sel_hi:[0,1]
	v_pk_mul_f32 v[50:51], v[64:65], v[50:51] op_sel_hi:[0,1]
	s_waitcnt lgkmcnt(0)
	v_mov_b32_e32 v1, v0
	s_nop 1
	v_permlane32_swap_b32_e32 v0, v1
	s_nop 0
	v_add_f32_e32 v0, v0, v1
	v_fmamk_f32 v0, v0, 0x3a000000, v232
	v_rsq_f32_e32 v66, v0
	v_pk_mul_f32 v[28:29], v[44:45], v[28:29] op_sel_hi:[0,1]
	v_pk_mul_f32 v[30:31], v[44:45], v[30:31] op_sel_hi:[0,1]
	v_pk_mul_f32 v[106:107], v[66:67], v[106:107] op_sel_hi:[0,1]
	v_pk_mul_f32 v[156:157], v[66:67], v[156:157] op_sel_hi:[0,1]
	v_pk_mul_f32 v[70:71], v[66:67], v[70:71] op_sel_hi:[0,1]
	v_pk_mul_f32 v[68:69], v[66:67], v[68:69] op_sel_hi:[0,1]
	v_pk_mul_f32 v[48:49], v[66:67], v[48:49] op_sel_hi:[0,1]
	v_pk_mul_f32 v[46:47], v[66:67], v[46:47] op_sel_hi:[0,1]
	s_waitcnt vmcnt(9)
	v_pk_mul_f32 v[162:163], v[162:163], v[180:181]
	v_pk_mul_f32 v[100:101], v[100:101], v[182:183]
	v_pk_add_f32 v[168:169], v[190:191], 1.0 op_sel_hi:[1,0]
	v_pk_add_f32 v[170:171], v[188:189], 1.0 op_sel_hi:[1,0]
	v_pk_fma_f32 v[100:101], v[100:101], v[168:169], v[186:187]
	v_pk_fma_f32 v[162:163], v[162:163], v[170:171], v[184:185]
	v_pk_mul_f32 v[160:161], v[160:161], v[180:181]
	v_cvt_pk_bf16_f32 v162, v162, v163
	v_cvt_pk_bf16_f32 v163, v100, v101
	v_lshl_add_u64 v[100:101], s[14:15], 0, v[18:19]
	v_pk_mul_f32 v[102:103], v[102:103], v[182:183]
	v_add_co_u32_e32 v100, vcc, s30, v100
	v_pk_fma_f32 v[102:103], v[102:103], v[168:169], v[186:187]
	v_pk_fma_f32 v[160:161], v[160:161], v[170:171], v[184:185]
	v_addc_co_u32_e32 v101, vcc, 0, v101, vcc
	v_cvt_pk_bf16_f32 v160, v160, v161
	v_cvt_pk_bf16_f32 v161, v102, v103
	v_lshl_add_u64 v[102:103], s[8:9], 0, v[18:19]
	v_pk_mul_f32 v[158:159], v[180:181], v[158:159]
	v_pk_mul_f32 v[104:105], v[182:183], v[104:105]
	v_pk_mul_f32 v[180:181], v[180:181], v[156:157]
	v_pk_mul_f32 v[182:183], v[182:183], v[106:107]
	v_add_co_u32_e32 v102, vcc, s30, v102
	v_pk_fma_f32 v[104:105], v[104:105], v[168:169], v[186:187]
	v_pk_fma_f32 v[158:159], v[158:159], v[170:171], v[184:185]
	v_pk_fma_f32 v[186:187], v[168:169], v[182:183], v[186:187]
	v_pk_fma_f32 v[184:185], v[170:171], v[180:181], v[184:185]
	v_addc_co_u32_e32 v103, vcc, 0, v103, vcc
	v_cvt_pk_bf16_f32 v158, v158, v159
	v_cvt_pk_bf16_f32 v159, v104, v105
	v_lshl_add_u64 v[104:105], v[26:27], 0, s[18:19]
	v_cvt_pk_bf16_f32 v184, v184, v185
	v_cvt_pk_bf16_f32 v185, v186, v187
	v_lshl_add_u64 v[106:107], v[26:27], 0, s[22:23]
	global_store_dwordx2 v[100:101], v[162:163], off
	global_store_dwordx2 v[102:103], v[160:161], off
	global_store_dwordx2 v[104:105], v[158:159], off
	global_store_dwordx2 v[106:107], v[184:185], off
	global_load_dwordx4 v[180:183], v[10:11], off
	global_load_dwordx4 v[184:187], v[252:253], off
	global_load_dwordx4 v[188:191], v[250:251], off
	s_nop 0
	s_cselect_b64 s[18:19], -1, 0
	s_add_u32 s8, s8, s10
	s_addc_u32 s9, s9, s11
	s_add_u32 s12, s12, s10
	s_addc_u32 s13, s13, s11
	s_add_u32 s14, s14, s10
	s_addc_u32 s15, s15, s11
	s_add_u32 s16, s16, s10
	s_addc_u32 s17, s17, s11
	s_waitcnt vmcnt(13)
	v_pk_mul_f32 v[134:135], v[134:135], v[196:197]
	v_pk_mul_f32 v[132:133], v[132:133], v[198:199]
	v_pk_add_f32 v[206:207], v[206:207], 1.0 op_sel_hi:[1,0]
	v_pk_add_f32 v[204:205], v[204:205], 1.0 op_sel_hi:[1,0]
	v_pk_fma_f32 v[132:133], v[132:133], v[206:207], v[202:203]
	v_pk_fma_f32 v[134:135], v[134:135], v[204:205], v[200:201]
	s_nop 0
	v_cvt_pk_bf16_f32 v134, v134, v135
	v_cvt_pk_bf16_f32 v135, v132, v133
	global_store_dwordx2 v[100:101], v[134:135], off offset:512
	v_pk_mul_f32 v[132:133], v[54:55], v[140:141] op_sel_hi:[0,1]
	v_pk_mul_f32 v[134:135], v[54:55], v[142:143] op_sel_hi:[0,1]
	v_pk_mul_f32 v[134:135], v[134:135], v[196:197]
	v_pk_mul_f32 v[132:133], v[132:133], v[198:199]
	v_pk_fma_f32 v[134:135], v[134:135], v[204:205], v[200:201]
	v_pk_fma_f32 v[132:133], v[132:133], v[206:207], v[202:203]
	v_cvt_pk_bf16_f32 v134, v134, v135
	v_cvt_pk_bf16_f32 v135, v132, v133
	global_store_dwordx2 v[102:103], v[134:135], off offset:512
	v_pk_mul_f32 v[132:133], v[64:65], v[148:149] op_sel_hi:[0,1]
	v_pk_mul_f32 v[134:135], v[64:65], v[150:151] op_sel_hi:[0,1]
	v_pk_mul_f32 v[134:135], v[134:135], v[196:197]
	v_pk_mul_f32 v[132:133], v[132:133], v[198:199]
	v_pk_fma_f32 v[134:135], v[134:135], v[204:205], v[200:201]
	v_pk_fma_f32 v[132:133], v[132:133], v[206:207], v[202:203]
	v_cvt_pk_bf16_f32 v134, v134, v135
	v_cvt_pk_bf16_f32 v135, v132, v133
	global_store_dwordx2 v[104:105], v[134:135], off offset:512
	v_pk_mul_f32 v[132:133], v[66:67], v[152:153] op_sel_hi:[0,1]
	v_pk_mul_f32 v[134:135], v[66:67], v[154:155] op_sel_hi:[0,1]
	v_pk_mul_f32 v[196:197], v[196:197], v[134:135]
	v_pk_mul_f32 v[198:199], v[198:199], v[132:133]
	v_pk_fma_f32 v[196:197], v[196:197], v[204:205], v[200:201]
	v_pk_fma_f32 v[198:199], v[198:199], v[206:207], v[202:203]
	v_cvt_pk_bf16_f32 v196, v196, v197
	v_cvt_pk_bf16_f32 v197, v198, v199
	global_store_dwordx2 v[106:107], v[196:197], off offset:512
	global_load_dwordx4 v[196:199], v[12:13], off
	global_load_dwordx4 v[200:203], v[250:251], off offset:1024
	global_load_dwordx4 v[204:207], v[252:253], off offset:1024
	s_nop 0
	s_waitcnt vmcnt(17)
	v_pk_mul_f32 v[116:117], v[116:117], v[208:209]
	v_pk_mul_f32 v[118:119], v[118:119], v[210:211]
	v_pk_add_f32 v[220:221], v[220:221], 1.0 op_sel_hi:[1,0]
	v_pk_add_f32 v[218:219], v[218:219], 1.0 op_sel_hi:[1,0]
	v_pk_fma_f32 v[118:119], v[118:119], v[220:221], v[214:215]
	v_pk_fma_f32 v[116:117], v[116:117], v[218:219], v[212:213]
	s_nop 0
	v_cvt_pk_bf16_f32 v116, v116, v117
	v_cvt_pk_bf16_f32 v117, v118, v119
	global_store_dwordx2 v[100:101], v[116:117], off offset:1024
	v_pk_mul_f32 v[116:117], v[54:55], v[126:127] op_sel_hi:[0,1]
	v_pk_mul_f32 v[118:119], v[54:55], v[124:125] op_sel_hi:[0,1]
	v_pk_mul_f32 v[118:119], v[118:119], v[208:209]
	v_pk_mul_f32 v[116:117], v[116:117], v[210:211]
	v_pk_fma_f32 v[118:119], v[118:119], v[218:219], v[212:213]
	v_pk_fma_f32 v[116:117], v[116:117], v[220:221], v[214:215]
	v_cvt_pk_bf16_f32 v118, v118, v119
	v_cvt_pk_bf16_f32 v119, v116, v117
	global_store_dwordx2 v[102:103], v[118:119], off offset:1024
	v_pk_mul_f32 v[116:117], v[64:65], v[138:139] op_sel_hi:[0,1]
	v_pk_mul_f32 v[118:119], v[64:65], v[136:137] op_sel_hi:[0,1]
	v_pk_mul_f32 v[118:119], v[118:119], v[208:209]
	v_pk_mul_f32 v[116:117], v[116:117], v[210:211]
	v_pk_fma_f32 v[118:119], v[118:119], v[218:219], v[212:213]
	v_pk_fma_f32 v[116:117], v[116:117], v[220:221], v[214:215]
	v_cvt_pk_bf16_f32 v118, v118, v119
	v_cvt_pk_bf16_f32 v119, v116, v117
	global_store_dwordx2 v[104:105], v[118:119], off offset:1024
	v_pk_mul_f32 v[116:117], v[66:67], v[146:147] op_sel_hi:[0,1]
	v_pk_mul_f32 v[118:119], v[66:67], v[144:145] op_sel_hi:[0,1]
	v_pk_mul_f32 v[208:209], v[118:119], v[208:209]
	v_pk_mul_f32 v[210:211], v[116:117], v[210:211]
	v_pk_fma_f32 v[208:209], v[208:209], v[218:219], v[212:213]
	v_pk_fma_f32 v[210:211], v[210:211], v[220:221], v[214:215]
	v_cvt_pk_bf16_f32 v208, v208, v209
	v_cvt_pk_bf16_f32 v209, v210, v211
	global_store_dwordx2 v[106:107], v[208:209], off offset:1024
	global_load_dwordx4 v[208:211], v[14:15], off
	global_load_dwordx4 v[212:215], v[250:251], off offset:2048
	global_load_dwordx4 v[218:221], v[252:253], off offset:2048
	s_nop 0
	s_waitcnt vmcnt(21)
	v_pk_mul_f32 v[108:109], v[108:109], v[222:223]
	v_pk_mul_f32 v[110:111], v[110:111], v[224:225]
	v_pk_add_f32 v[244:245], v[244:245], 1.0 op_sel_hi:[1,0]
	v_pk_add_f32 v[242:243], v[242:243], 1.0 op_sel_hi:[1,0]
	v_pk_fma_f32 v[110:111], v[110:111], v[244:245], v[228:229]
	v_pk_fma_f32 v[108:109], v[108:109], v[242:243], v[226:227]
	s_nop 0
	v_cvt_pk_bf16_f32 v108, v108, v109
	v_cvt_pk_bf16_f32 v109, v110, v111
	global_store_dwordx2 v[100:101], v[108:109], off offset:1536
	v_pk_mul_f32 v[108:109], v[54:55], v[114:115] op_sel_hi:[0,1]
	v_pk_mul_f32 v[110:111], v[54:55], v[112:113] op_sel_hi:[0,1]
	v_pk_mul_f32 v[110:111], v[110:111], v[222:223]
	v_pk_mul_f32 v[108:109], v[108:109], v[224:225]
	v_pk_fma_f32 v[110:111], v[110:111], v[242:243], v[226:227]
	v_pk_fma_f32 v[108:109], v[108:109], v[244:245], v[228:229]
	v_cvt_pk_bf16_f32 v110, v110, v111
	v_cvt_pk_bf16_f32 v111, v108, v109
	global_store_dwordx2 v[102:103], v[110:111], off offset:1536
	v_pk_mul_f32 v[108:109], v[64:65], v[122:123] op_sel_hi:[0,1]
	v_pk_mul_f32 v[110:111], v[64:65], v[120:121] op_sel_hi:[0,1]
	v_pk_mul_f32 v[110:111], v[110:111], v[222:223]
	v_pk_mul_f32 v[108:109], v[108:109], v[224:225]
	v_pk_fma_f32 v[110:111], v[110:111], v[242:243], v[226:227]
	v_pk_fma_f32 v[108:109], v[108:109], v[244:245], v[228:229]
	v_cvt_pk_bf16_f32 v110, v110, v111
	v_cvt_pk_bf16_f32 v111, v108, v109
	global_store_dwordx2 v[104:105], v[110:111], off offset:1536
	v_pk_mul_f32 v[108:109], v[66:67], v[130:131] op_sel_hi:[0,1]
	v_pk_mul_f32 v[110:111], v[66:67], v[128:129] op_sel_hi:[0,1]
	v_pk_mul_f32 v[222:223], v[110:111], v[222:223]
	v_pk_mul_f32 v[224:225], v[108:109], v[224:225]
	v_add_co_u32_e32 v108, vcc, s77, v166
	v_pk_fma_f32 v[224:225], v[224:225], v[244:245], v[228:229]
	v_pk_fma_f32 v[222:223], v[222:223], v[242:243], v[226:227]
	v_addc_co_u32_e32 v109, vcc, 0, v167, vcc
	v_cvt_pk_bf16_f32 v222, v222, v223
	v_cvt_pk_bf16_f32 v223, v224, v225
	v_add_co_u32_e32 v110, vcc, s77, v164
	global_store_dwordx2 v[106:107], v[222:223], off offset:1536
	global_load_dwordx4 v[222:225], v[16:17], off
	global_load_dwordx4 v[226:229], v[250:251], off offset:3072
	global_load_dwordx4 v[242:245], v[252:253], off offset:3072
	s_nop 0
	v_addc_co_u32_e32 v111, vcc, 0, v165, vcc
	v_subrev_co_u32_e32 v175, vcc, 1, v175
	s_waitcnt vmcnt(21)
	v_pk_mul_f32 v[84:85], v[84:85], v[180:181]
	v_pk_add_f32 v[112:113], v[186:187], 1.0 op_sel_hi:[1,0]
	v_pk_add_f32 v[184:185], v[184:185], 1.0 op_sel_hi:[1,0]
	v_pk_mul_f32 v[86:87], v[86:87], v[182:183]
	v_pk_fma_f32 v[84:85], v[84:85], v[184:185], v[188:189]
	v_pk_fma_f32 v[86:87], v[86:87], v[112:113], v[190:191]
	v_cvt_pk_bf16_f32 v84, v84, v85
	v_cvt_pk_bf16_f32 v85, v86, v87
	global_store_dwordx2 v[100:101], v[84:85], off offset:2048
	v_pk_mul_f32 v[84:85], v[54:55], v[88:89] op_sel_hi:[0,1]
	v_pk_mul_f32 v[86:87], v[54:55], v[90:91] op_sel_hi:[0,1]
	v_pk_mul_f32 v[86:87], v[86:87], v[180:181]
	v_pk_mul_f32 v[84:85], v[84:85], v[182:183]
	v_pk_fma_f32 v[86:87], v[86:87], v[184:185], v[188:189]
	v_pk_fma_f32 v[84:85], v[84:85], v[112:113], v[190:191]
	v_cvt_pk_bf16_f32 v86, v86, v87
	v_cvt_pk_bf16_f32 v87, v84, v85
	global_store_dwordx2 v[102:103], v[86:87], off offset:2048
	v_pk_mul_f32 v[84:85], v[64:65], v[92:93] op_sel_hi:[0,1]
	v_pk_mul_f32 v[86:87], v[64:65], v[94:95] op_sel_hi:[0,1]
	v_pk_mul_f32 v[86:87], v[86:87], v[180:181]
	v_pk_mul_f32 v[84:85], v[84:85], v[182:183]
	v_pk_fma_f32 v[86:87], v[86:87], v[184:185], v[188:189]
	v_pk_fma_f32 v[84:85], v[84:85], v[112:113], v[190:191]
	v_cvt_pk_bf16_f32 v86, v86, v87
	v_cvt_pk_bf16_f32 v87, v84, v85
	global_store_dwordx2 v[104:105], v[86:87], off offset:2048
	v_pk_mul_f32 v[84:85], v[66:67], v[96:97] op_sel_hi:[0,1]
	v_pk_mul_f32 v[86:87], v[66:67], v[98:99] op_sel_hi:[0,1]
	v_pk_mul_f32 v[180:181], v[86:87], v[180:181]
	v_pk_mul_f32 v[182:183], v[84:85], v[182:183]
	v_pk_fma_f32 v[180:181], v[180:181], v[184:185], v[188:189]
	v_pk_fma_f32 v[182:183], v[182:183], v[112:113], v[190:191]
	v_cvt_pk_bf16_f32 v180, v180, v181
	v_cvt_pk_bf16_f32 v181, v182, v183
	global_store_dwordx2 v[106:107], v[180:181], off offset:2048
	s_nop 0
	s_waitcnt vmcnt(18)
	v_pk_mul_f32 v[80:81], v[80:81], v[196:197]
	v_pk_mul_f32 v[82:83], v[82:83], v[198:199]
	v_pk_add_f32 v[84:85], v[206:207], 1.0 op_sel_hi:[1,0]
	v_pk_add_f32 v[204:205], v[204:205], 1.0 op_sel_hi:[1,0]
	v_pk_mul_f32 v[76:77], v[76:77], v[196:197]
	v_pk_mul_f32 v[78:79], v[78:79], v[198:199]
	v_pk_mul_f32 v[72:73], v[72:73], v[196:197]
	v_pk_mul_f32 v[74:75], v[74:75], v[198:199]
	v_pk_mul_f32 v[196:197], v[68:69], v[196:197]
	v_pk_mul_f32 v[198:199], v[70:71], v[198:199]
	v_pk_fma_f32 v[82:83], v[82:83], v[84:85], v[202:203]
	v_pk_fma_f32 v[80:81], v[80:81], v[204:205], v[200:201]
	v_pk_fma_f32 v[78:79], v[78:79], v[84:85], v[202:203]
	v_pk_fma_f32 v[76:77], v[76:77], v[204:205], v[200:201]
	v_pk_fma_f32 v[74:75], v[74:75], v[84:85], v[202:203]
	v_pk_fma_f32 v[72:73], v[72:73], v[204:205], v[200:201]
	v_pk_fma_f32 v[202:203], v[198:199], v[84:85], v[202:203]
	v_pk_fma_f32 v[200:201], v[196:197], v[204:205], v[200:201]
	v_cvt_pk_bf16_f32 v80, v80, v81
	v_cvt_pk_bf16_f32 v81, v82, v83
	v_cvt_pk_bf16_f32 v76, v76, v77
	v_cvt_pk_bf16_f32 v77, v78, v79
	v_cvt_pk_bf16_f32 v72, v72, v73
	v_cvt_pk_bf16_f32 v73, v74, v75
	v_cvt_pk_bf16_f32 v200, v200, v201
	v_cvt_pk_bf16_f32 v201, v202, v203
	global_store_dwordx2 v[100:101], v[80:81], off offset:2560
	global_store_dwordx2 v[102:103], v[76:77], off offset:2560
	global_store_dwordx2 v[104:105], v[72:73], off offset:2560
	global_store_dwordx2 v[106:107], v[200:201], off offset:2560
	s_nop 0
	s_waitcnt vmcnt(15)
	v_pk_mul_f32 v[56:57], v[56:57], v[208:209]
	v_pk_mul_f32 v[58:59], v[58:59], v[210:211]
	v_pk_add_f32 v[220:221], v[220:221], 1.0 op_sel_hi:[1,0]
	v_pk_add_f32 v[218:219], v[218:219], 1.0 op_sel_hi:[1,0]
	v_pk_fma_f32 v[58:59], v[58:59], v[220:221], v[214:215]
	v_pk_fma_f32 v[56:57], v[56:57], v[218:219], v[212:213]
	v_pk_mul_f32 v[50:51], v[50:51], v[208:209]
	v_cvt_pk_bf16_f32 v56, v56, v57
	v_cvt_pk_bf16_f32 v57, v58, v59
	global_store_dwordx2 v[100:101], v[56:57], off offset:3072
	v_pk_mul_f32 v[56:57], v[54:55], v[62:63] op_sel_hi:[0,1]
	v_pk_mul_f32 v[58:59], v[54:55], v[60:61] op_sel_hi:[0,1]
	v_pk_mul_f32 v[58:59], v[58:59], v[208:209]
	v_pk_mul_f32 v[56:57], v[56:57], v[210:211]
	v_pk_mul_f32 v[52:53], v[52:53], v[210:211]
	v_pk_mul_f32 v[208:209], v[46:47], v[208:209]
	v_pk_mul_f32 v[210:211], v[48:49], v[210:211]
	v_pk_fma_f32 v[56:57], v[56:57], v[220:221], v[214:215]
	v_pk_fma_f32 v[58:59], v[58:59], v[218:219], v[212:213]
	v_pk_fma_f32 v[52:53], v[52:53], v[220:221], v[214:215]
	v_pk_fma_f32 v[50:51], v[50:51], v[218:219], v[212:213]
	v_pk_fma_f32 v[210:211], v[210:211], v[220:221], v[214:215]
	v_pk_fma_f32 v[208:209], v[208:209], v[218:219], v[212:213]
	v_cvt_pk_bf16_f32 v58, v58, v59
	v_cvt_pk_bf16_f32 v59, v56, v57
	v_cvt_pk_bf16_f32 v50, v50, v51
	v_cvt_pk_bf16_f32 v51, v52, v53
	v_cvt_pk_bf16_f32 v208, v208, v209
	v_cvt_pk_bf16_f32 v209, v210, v211
	global_store_dwordx2 v[102:103], v[58:59], off offset:3072
	global_store_dwordx2 v[104:105], v[50:51], off offset:3072
	global_store_dwordx2 v[106:107], v[208:209], off offset:3072
	s_nop 0
	s_waitcnt vmcnt(12)
	v_pk_mul_f32 v[30:31], v[30:31], v[222:223]
	v_pk_mul_f32 v[28:29], v[28:29], v[224:225]
	v_pk_add_f32 v[244:245], v[244:245], 1.0 op_sel_hi:[1,0]
	v_pk_add_f32 v[242:243], v[242:243], 1.0 op_sel_hi:[1,0]
	v_pk_fma_f32 v[28:29], v[28:29], v[244:245], v[228:229]
	v_pk_fma_f32 v[30:31], v[30:31], v[242:243], v[226:227]
	s_nop 0
	v_cvt_pk_bf16_f32 v30, v30, v31
	v_cvt_pk_bf16_f32 v31, v28, v29
	global_store_dwordx2 v[100:101], v[30:31], off offset:3584
	v_pk_mul_f32 v[28:29], v[54:55], v[32:33] op_sel_hi:[0,1]
	v_pk_mul_f32 v[30:31], v[54:55], v[34:35] op_sel_hi:[0,1]
	v_pk_mul_f32 v[30:31], v[30:31], v[222:223]
	v_pk_mul_f32 v[28:29], v[28:29], v[224:225]
	v_pk_fma_f32 v[30:31], v[30:31], v[242:243], v[226:227]
	v_pk_fma_f32 v[28:29], v[28:29], v[244:245], v[228:229]
	v_cvt_pk_bf16_f32 v30, v30, v31
	v_cvt_pk_bf16_f32 v31, v28, v29
	global_store_dwordx2 v[102:103], v[30:31], off offset:3584
	v_pk_mul_f32 v[28:29], v[64:65], v[36:37] op_sel_hi:[0,1]
	v_pk_mul_f32 v[30:31], v[64:65], v[38:39] op_sel_hi:[0,1]
	v_pk_mul_f32 v[30:31], v[30:31], v[222:223]
	v_pk_mul_f32 v[28:29], v[28:29], v[224:225]
	v_pk_fma_f32 v[30:31], v[30:31], v[242:243], v[226:227]
	v_pk_fma_f32 v[28:29], v[28:29], v[244:245], v[228:229]
	v_cvt_pk_bf16_f32 v30, v30, v31
	v_cvt_pk_bf16_f32 v31, v28, v29
	global_store_dwordx2 v[104:105], v[30:31], off offset:3584
	v_pk_mul_f32 v[28:29], v[66:67], v[40:41] op_sel_hi:[0,1]
	v_pk_mul_f32 v[30:31], v[66:67], v[42:43] op_sel_hi:[0,1]
	v_pk_mul_f32 v[222:223], v[30:31], v[222:223]
	v_pk_mul_f32 v[224:225], v[28:29], v[224:225]
	v_pk_fma_f32 v[222:223], v[222:223], v[242:243], v[226:227]
	v_pk_fma_f32 v[224:225], v[224:225], v[244:245], v[228:229]
	v_cvt_pk_bf16_f32 v222, v222, v223
	v_cvt_pk_bf16_f32 v223, v224, v225
	global_store_dwordx2 v[106:107], v[222:223], off offset:3584
	v_cndmask_b32_e64 v0, 0, 1, vcc
	v_cndmask_b32_e64 v1, 0, 1, s[18:19]
	v_cndmask_b32_e64 v0, v1, v0, s[2:3]
	v_and_b32_e32 v0, 1, v0
	v_cmp_eq_u32_e32 vcc, 1, v0
	s_cbranch_vccnz .LBB0_1793
